# v15
# baseline (speedup 1.0000x reference)
.LBB0_110:
	s_or_b64 exec, exec, s[10:11]
	s_add_i32 s10, s2, 0x80
	s_add_i32 s16, s0, 0x80
	s_ashr_i32 s11, s10, 31
	s_ashr_i32 s1, s0, 31
	s_ashr_i32 s3, s2, 31
	s_ashr_i32 s17, s16, 31
	s_lshl_b64 s[10:11], s[10:11], 12
	s_lshl_b64 s[12:13], s[0:1], 12
	s_lshl_b64 s[14:15], s[2:3], 12
	s_lshl_b64 s[16:17], s[16:17], 12
	s_add_u32 s12, s38, s12
	s_addc_u32 s13, s39, s13
	s_add_u32 s14, s38, s14
	s_addc_u32 s15, s39, s15
	s_add_u32 s16, s38, s16
	s_addc_u32 s17, s39, s17
	s_add_u32 s18, s38, s10
	v_mov_b32_e32 v0, 0
	s_addc_u32 s19, s39, s11
	s_mov_b32 s21, -2
	v_mov_b32_e32 v1, v0
	v_mov_b32_e32 v2, v0
	v_mov_b32_e32 v3, v0
	v_mov_b32_e32 v4, v0
	v_mov_b32_e32 v5, v0
	v_mov_b32_e32 v6, v0
	v_mov_b32_e32 v7, v0
	v_mov_b32_e32 v8, v0
	v_mov_b32_e32 v9, v0
	v_mov_b32_e32 v10, v0
	v_mov_b32_e32 v11, v0
	v_mov_b32_e32 v12, v0
	v_mov_b32_e32 v13, v0
	v_mov_b32_e32 v14, v0
	v_mov_b32_e32 v15, v0
	v_mov_b32_e32 v16, v0
	v_mov_b32_e32 v17, v0
	v_mov_b32_e32 v18, v0
	v_mov_b32_e32 v19, v0
	v_mov_b32_e32 v20, v0
	v_mov_b32_e32 v21, v0
	v_mov_b32_e32 v22, v0
	v_mov_b32_e32 v23, v0
	v_mov_b32_e32 v24, v0
	v_mov_b32_e32 v25, v0
	v_mov_b32_e32 v26, v0
	v_mov_b32_e32 v27, v0
	v_mov_b32_e32 v28, v0
	v_mov_b32_e32 v29, v0
	v_mov_b32_e32 v30, v0
	v_mov_b32_e32 v31, v0
	v_mov_b32_e32 v32, v0
	v_mov_b32_e32 v33, v0
	v_mov_b32_e32 v34, v0
	v_mov_b32_e32 v35, v0
	v_mov_b32_e32 v36, v0
	v_mov_b32_e32 v37, v0
	v_mov_b32_e32 v38, v0
	v_mov_b32_e32 v39, v0
	v_mov_b32_e32 v40, v0
	v_mov_b32_e32 v41, v0
	v_mov_b32_e32 v42, v0
	v_mov_b32_e32 v43, v0
	v_mov_b32_e32 v44, v0
	v_mov_b32_e32 v45, v0
	v_mov_b32_e32 v46, v0
	v_mov_b32_e32 v47, v0
	v_mov_b32_e32 v48, v0
	v_mov_b32_e32 v49, v0
	v_mov_b32_e32 v50, v0
	v_mov_b32_e32 v51, v0
	v_mov_b32_e32 v52, v0
	v_mov_b32_e32 v53, v0
	v_mov_b32_e32 v54, v0
	v_mov_b32_e32 v55, v0
	v_mov_b32_e32 v56, v0
	v_mov_b32_e32 v57, v0
	v_mov_b32_e32 v58, v0
	v_mov_b32_e32 v59, v0
	v_mov_b32_e32 v60, v0
	v_mov_b32_e32 v61, v0
	v_mov_b32_e32 v62, v0
	v_mov_b32_e32 v63, v0
	v_mov_b32_e32 v64, v0
	v_mov_b32_e32 v65, v0
	v_mov_b32_e32 v66, v0
	v_mov_b32_e32 v67, v0
	v_mov_b32_e32 v68, v0
	v_mov_b32_e32 v69, v0
	v_mov_b32_e32 v70, v0
	v_mov_b32_e32 v71, v0
	v_mov_b32_e32 v72, v0
	v_mov_b32_e32 v73, v0
	v_mov_b32_e32 v74, v0
	v_mov_b32_e32 v75, v0
	v_mov_b32_e32 v76, v0
	v_mov_b32_e32 v77, v0
	v_mov_b32_e32 v78, v0
	v_mov_b32_e32 v79, v0
	v_mov_b32_e32 v80, v0
	v_mov_b32_e32 v81, v0
	v_mov_b32_e32 v82, v0
	v_mov_b32_e32 v83, v0
	v_mov_b32_e32 v84, v0
	v_mov_b32_e32 v85, v0
	v_mov_b32_e32 v86, v0
	v_mov_b32_e32 v87, v0
	v_mov_b32_e32 v88, v0
	v_mov_b32_e32 v89, v0
	v_mov_b32_e32 v90, v0
	v_mov_b32_e32 v91, v0
	v_mov_b32_e32 v92, v0
	v_mov_b32_e32 v93, v0
	v_mov_b32_e32 v94, v0
	v_mov_b32_e32 v95, v0
	v_mov_b32_e32 v96, v0
	v_mov_b32_e32 v97, v0
	v_mov_b32_e32 v98, v0
	v_mov_b32_e32 v99, v0
	v_mov_b32_e32 v100, v0
	v_mov_b32_e32 v101, v0
	v_mov_b32_e32 v102, v0
	v_mov_b32_e32 v103, v0
	v_mov_b32_e32 v104, v0
	v_mov_b32_e32 v105, v0
	v_mov_b32_e32 v106, v0
	v_mov_b32_e32 v107, v0
	v_mov_b32_e32 v108, v0
	v_mov_b32_e32 v109, v0
	v_mov_b32_e32 v110, v0
	v_mov_b32_e32 v111, v0
	v_mov_b32_e32 v112, v0
	v_mov_b32_e32 v113, v0
	v_mov_b32_e32 v114, v0
	v_mov_b32_e32 v115, v0
	v_mov_b32_e32 v116, v0
	v_mov_b32_e32 v117, v0
	v_mov_b32_e32 v118, v0
	v_mov_b32_e32 v119, v0
	v_mov_b32_e32 v120, v0
	v_mov_b32_e32 v121, v0
	v_mov_b32_e32 v122, v0
	v_mov_b32_e32 v123, v0
	v_mov_b32_e32 v124, v0
	v_mov_b32_e32 v125, v0
	v_mov_b32_e32 v126, v0
	v_mov_b32_e32 v127, v0
	s_barrier
	s_barrier
	.p2align 6

.LBB0_185:
	s_or_b64 exec, exec, s[0:1]
	v_readlane_b32 s0, v247, 45
	v_readlane_b32 s1, v247, 46
	s_andn2_b64 vcc, exec, s[0:1]
	s_barrier
	s_cbranch_vccnz .LBB0_347
	v_readfirstlane_b32 s6, v187
	s_bfe_u32 s6, s6, 0x40006
	s_cmp_lt_u32 s6, 4
	s_cbranch_scc1 .Lprio_done_diff
	s_setprio 1
.Lprio_done_diff:
	v_mov_b32_e32 v2, v187
	v_readlane_b32 s6, v247, 48
	v_readfirstlane_b32 s0, v2
	s_ashr_i32 s0, s0, 1
	v_readlane_b32 s7, v247, 49
	v_mov_b32_e32 v0, s0
	s_movk_i32 s0, 0xffe0
	v_bfi_b32 v0, s0, v0, v2
	v_ashrrev_i32_e32 v1, 31, v0
	v_lshlrev_b64 v[0:1], 8, v[0:1]
	v_lshrrev_b32_e32 v3, 1, v2
	v_lshl_add_u64 v[0:1], s[6:7], 0, v[0:1]
	v_and_b32_e32 v184, 16, v3
	v_lshl_add_u64 v[0:1], v[0:1], 0, v[184:185]
	global_load_dwordx4 v[124:127], v[0:1], off
	global_load_dwordx4 v[120:123], v[0:1], off offset:32
	global_load_dwordx4 v[116:119], v[0:1], off offset:64
	global_load_dwordx4 v[112:115], v[0:1], off offset:96
	global_load_dwordx4 v[108:111], v[0:1], off offset:128
	global_load_dwordx4 v[104:107], v[0:1], off offset:160
	global_load_dwordx4 v[100:103], v[0:1], off offset:192
	global_load_dwordx4 v[96:99], v[0:1], off offset:224
	v_ashrrev_i32_e32 v0, 4, v2
	v_lshlrev_b32_e32 v1, 4, v2
	v_and_b32_e32 v2, 0x70, v2
	s_movk_i32 s0, 0xf0
	v_and_b32_e32 v184, 0xf0, v1
	v_bitop3_b32 v9, v1, v2, s0 bitop3:0x6c
	v_ashrrev_i32_e32 v1, 31, v0
	v_readlane_b32 s4, v247, 56
	v_lshlrev_b32_e32 v8, 8, v0
	v_lshlrev_b64 v[0:1], 8, v[0:1]
	v_readlane_b32 s5, v247, 57
	s_mov_b64 s[0:1], 0x2000
	v_readlane_b32 s2, v247, 52
	v_lshl_add_u64 v[2:3], s[4:5], 0, v[0:1]
	v_lshl_add_u64 v[2:3], v[2:3], 0, v[184:185]
	v_lshl_add_u64 v[4:5], v[0:1], 0, s[0:1]
	v_readlane_b32 s3, v247, 53
	global_load_dwordx4 v[128:131], v[2:3], off
	v_lshl_add_u64 v[2:3], s[4:5], 0, v[4:5]
	v_lshl_add_u64 v[0:1], s[2:3], 0, v[0:1]
	v_lshl_add_u64 v[2:3], v[2:3], 0, v[184:185]
	v_lshl_add_u64 v[0:1], v[0:1], 0, v[184:185]
	v_lshl_add_u64 v[4:5], s[2:3], 0, v[4:5]
	global_load_dwordx4 v[132:135], v[2:3], off
	v_lshl_add_u64 v[4:5], v[4:5], 0, v[184:185]
	global_load_dwordx4 v[0:3], v[0:1], off
	v_readlane_b32 s16, v247, 58
	global_load_dwordx4 v[4:7], v[4:5], off
	s_waitcnt vmcnt(0)
	v_readlane_b32 s23, v247, 47
	v_readlane_b32 s17, v247, 59
	s_mov_b64 s[0:1], s[4:5]
	v_readlane_b32 s4, v246, 1
	v_add3_u32 v8, 0, v8, v9
	s_mov_b32 s20, 0
	s_mov_b32 s21, s4
	s_mov_b32 s22, s23
	s_mov_b64 s[10:11], s[16:17]
	s_mov_b64 s[8:9], s[0:1]
	s_mov_b64 s[12:13], s[2:3]
	v_readlane_b32 s5, v246, 2
	s_waitcnt vmcnt(1)
	ds_write_b128 v8, v[0:3] offset:32768
	s_waitcnt vmcnt(0)
	ds_write_b128 v8, v[4:7] offset:40960
	s_waitcnt lgkmcnt(0)
	s_barrier
	s_branch .LBB0_188

.LBB0_192:
	s_and_b32 s4, s4, 0x3fffffc0
	v_and_b32_e32 v49, 63, v171
	s_lshl_b32 s4, s4, 2
	s_lshr_b32 s23, s23, 6
	s_add_i32 s4, s4, 0
	v_lshlrev_b32_e32 v50, 8, v160
	v_and_b32_e32 v51, 0x70, v171
	v_lshlrev_b32_e32 v52, 4, v49
	s_add_i32 s23, s23, 4
	s_add_i32 s26, s4, 0x10000
	v_bitop3_b32 v51, v184, v50, v51 bitop3:0xde
	v_lshlrev_b32_e32 v50, 3, v49
	v_and_b32_e32 v52, 0xc0, v52
	v_lshlrev_b32_e32 v53, 1, v49
	v_and_or_b32 v52, v50, 24, v52
	v_and_b32_e32 v53, 32, v53
	v_and_b32_e32 v50, 0x100, v50
	s_cmp_lg_u32 0, -1
	v_or3_b32 v50, v52, v53, v50
	s_cselect_b32 s4, 0, 0
	v_add_u32_e32 v173, s4, v50
	v_max_f32_e32 v50, v17, v17
	v_max_f32_e32 v52, v16, v16
	v_max_f32_e32 v50, v52, v50
	v_max3_f32 v50, v50, v18, v19
	v_max3_f32 v50, v50, v20, v21
	v_max3_f32 v50, v50, v22, v23
	v_max3_f32 v50, v50, v24, v25
	v_max3_f32 v50, v50, v26, v27
	v_max3_f32 v50, v50, v28, v29
	v_max3_f32 v50, v50, v30, v31
	v_max3_f32 v50, v50, v0, v1
	v_max3_f32 v50, v50, v2, v3
	v_max3_f32 v50, v50, v4, v5
	v_max3_f32 v50, v50, v6, v7
	v_max3_f32 v50, v50, v8, v9
	v_max3_f32 v50, v50, v10, v11
	v_max3_f32 v50, v50, v12, v13
	v_max3_f32 v50, v50, v14, v15
	v_mov_b32_e32 v52, v50
	s_nop 1
	v_permlane32_swap_b32_e32 v50, v52
	v_max_f32_e32 v52, v52, v52
	v_max_f32_e32 v50, v50, v50
	v_max_f32_e32 v50, v50, v52
	v_add_f32_e32 v52, 0x7149f2ca, v50
	v_mul_f32_e32 v52, 0x3db504f3, v52
	v_max_f32_e32 v50, 0xf149f2ca, v50
	v_cmp_ge_f32_e32 vcc, s87, v52
	v_sub_f32_e32 v52, 0xf149f2ca, v50
	s_add_i32 s24, s19, 0xffffe01f
	v_mul_f32_e32 v52, 0x3e0293ee, v52
	v_exp_f32_e32 v52, v52
	s_cmp_eq_u64 vcc, exec
	s_cselect_b64 vcc, -1, 0
	v_cndmask_b32_e32 v186, v50, v203, vcc
	v_mul_f32_e32 v50, 0xbe0293ee, v186
	v_cndmask_b32_e64 v183, v52, 1.0, vcc
	v_mov_b32_e32 v52, v50
	v_fmamk_f32 v16, v16, 0x3e0293ee, v50
	v_fmamk_f32 v17, v17, 0x3e0293ee, v50
	v_fmamk_f32 v18, v18, 0x3e0293ee, v50
	v_fmamk_f32 v19, v19, 0x3e0293ee, v50
	v_fmamk_f32 v20, v20, 0x3e0293ee, v50
	v_fmamk_f32 v21, v21, 0x3e0293ee, v50
	v_fmamk_f32 v22, v22, 0x3e0293ee, v50
	v_fmamk_f32 v23, v23, 0x3e0293ee, v50
	v_fmamk_f32 v24, v24, 0x3e0293ee, v50
	v_fmamk_f32 v25, v25, 0x3e0293ee, v50
	v_fmamk_f32 v26, v26, 0x3e0293ee, v50
	v_fmamk_f32 v27, v27, 0x3e0293ee, v50
	v_fmamk_f32 v28, v28, 0x3e0293ee, v50
	v_fmamk_f32 v29, v29, 0x3e0293ee, v50
	v_fmamk_f32 v30, v30, 0x3e0293ee, v50
	v_fmac_f32_e32 v52, 0x3e0293ee, v31
	v_lshl_add_u64 v[166:167], s[0:1], 0, v[184:185]
	s_add_i32 s0, s19, 0xffffdf45
	v_pk_fma_f32 v[156:157], v[0:1], s[90:91], v[50:51] op_sel_hi:[1,0,0]
	v_exp_f32_e32 v216, v16
	v_exp_f32_e32 v219, v17
	v_exp_f32_e32 v213, v18
	v_exp_f32_e32 v217, v19
	v_exp_f32_e32 v212, v20
	v_exp_f32_e32 v214, v21
	v_exp_f32_e32 v210, v22
	v_exp_f32_e32 v211, v23
	v_exp_f32_e32 v207, v24
	v_exp_f32_e32 v209, v25
	v_exp_f32_e32 v206, v26
	v_exp_f32_e32 v208, v27
	v_exp_f32_e32 v195, v28
	v_exp_f32_e32 v197, v29
	v_exp_f32_e32 v194, v30
	v_exp_f32_e32 v196, v52
	v_add_u32_e32 v0, s0, v172
	s_waitcnt vmcnt(0)
	v_add_u32_e32 v176, 0, v51
	v_cmp_gt_u32_e64 s[4:5], 32, v49
	v_lshl_add_u32 v174, v48, 2, s26
	v_sub_u32_e32 v188, v0, v48
	v_mov_b32_e32 v48, v185
	v_mov_b32_e32 v49, v185
	v_pk_fma_f32 v[146:147], v[14:15], s[90:91], v[50:51] op_sel_hi:[1,0,0]
	v_pk_fma_f32 v[152:153], v[12:13], s[90:91], v[50:51] op_sel_hi:[1,0,0]
	v_pk_fma_f32 v[158:159], v[10:11], s[90:91], v[50:51] op_sel_hi:[1,0,0]
	v_pk_fma_f32 v[144:145], v[8:9], s[90:91], v[50:51] op_sel_hi:[1,0,0]
	v_pk_fma_f32 v[148:149], v[6:7], s[90:91], v[50:51] op_sel_hi:[1,0,0]
	v_pk_fma_f32 v[150:151], v[4:5], s[90:91], v[50:51] op_sel_hi:[1,0,0]
	v_pk_fma_f32 v[154:155], v[2:3], s[90:91], v[50:51] op_sel_hi:[1,0,0]
	s_waitcnt vmcnt(3)
	ds_write_b128 v181, v[32:35] offset:16384
	s_waitcnt vmcnt(2)
	ds_write_b128 v182, v[36:39] offset:16384
	s_waitcnt vmcnt(1)
	ds_write_b128 v176, v[40:43] offset:49152
	s_waitcnt vmcnt(0)
	ds_write_b128 v176, v[44:47] offset:57344
	v_mov_b32_e32 v50, v185
	v_mov_b32_e32 v51, v185
	v_mov_b32_e32 v52, v185
	v_mov_b32_e32 v53, v185
	v_mov_b32_e32 v54, v185
	v_mov_b32_e32 v55, v185
	v_mov_b32_e32 v56, v185
	v_mov_b32_e32 v57, v185
	v_mov_b32_e32 v58, v185
	v_mov_b32_e32 v59, v185
	v_mov_b32_e32 v60, v185
	v_mov_b32_e32 v61, v185
	v_mov_b32_e32 v62, v185
	v_mov_b32_e32 v63, v185
	v_mov_b64_e32 v[32:33], v[48:49]
	v_mov_b64_e32 v[16:17], v[48:49]
	v_mov_b64_e32 v[0:1], v[48:49]
	s_mov_b32 s25, 2
	v_lshl_add_u64 v[168:169], s[2:3], 0, v[184:185]
	v_lshl_add_u32 v175, v172, 2, s26
	v_mov_b32_e32 v177, 0
	s_movk_i32 s26, 0x7f
	v_mov_b64_e32 v[34:35], v[50:51]
	v_mov_b64_e32 v[36:37], v[52:53]
	v_mov_b64_e32 v[38:39], v[54:55]
	v_mov_b64_e32 v[40:41], v[56:57]
	v_mov_b64_e32 v[42:43], v[58:59]
	v_mov_b64_e32 v[44:45], v[60:61]
	v_mov_b64_e32 v[46:47], v[62:63]
	v_mov_b64_e32 v[18:19], v[50:51]
	v_mov_b64_e32 v[20:21], v[52:53]
	v_mov_b64_e32 v[22:23], v[54:55]
	v_mov_b64_e32 v[24:25], v[56:57]
	v_mov_b64_e32 v[26:27], v[58:59]
	v_mov_b64_e32 v[28:29], v[60:61]
	v_mov_b64_e32 v[30:31], v[62:63]
	v_mov_b64_e32 v[2:3], v[50:51]
	v_mov_b64_e32 v[4:5], v[52:53]
	v_mov_b64_e32 v[6:7], v[54:55]
	v_mov_b64_e32 v[8:9], v[56:57]
	v_mov_b64_e32 v[10:11], v[58:59]
	v_mov_b64_e32 v[12:13], v[60:61]
	v_mov_b64_e32 v[14:15], v[62:63]
	s_waitcnt lgkmcnt(0)
	s_barrier
	.p2align 6
.LBB0_193:
	ds_read_b128 v[64:67], v180 offset:49152
	ds_read_b128 v[68:71], v180 offset:57344
	ds_read_b128 v[128:131], v179 offset:49152
	s_waitcnt vmcnt(2)
	ds_read_b128 v[132:135], v179 offset:57344
	ds_read_b128 v[248:251], v165 offset:49152
	ds_read_b128 v[252:255], v165 offset:57344
	s_waitcnt vmcnt(1)
	v_exp_f32_e32 v136, v144
	v_add_f32_e32 v144, 0, v216
	s_waitcnt lgkmcnt(5)
	v_mfma_f32_32x32x16_bf16 v[80:95], v[64:67], v[124:127], 0
	v_add_f32_e32 v144, v219, v144
	v_add_f32_e32 v144, v213, v144
	v_add_f32_e32 v144, v217, v144
	v_add_f32_e32 v144, v212, v144
	v_add_f32_e32 v144, v214, v144
	v_add_f32_e32 v144, v210, v144
	v_add_f32_e32 v144, v211, v144
	s_waitcnt lgkmcnt(4)
	v_mfma_f32_32x32x16_bf16 v[64:79], v[68:71], v[124:127], 0
	v_add_f32_e32 v144, v207, v144
	v_add_f32_e32 v144, v209, v144
	v_add_f32_e32 v144, v206, v144
	v_add_f32_e32 v144, v208, v144
	v_add_f32_e32 v144, v195, v144
	v_add_f32_e32 v144, v197, v144
	v_add_f32_e32 v144, v194, v144
	s_waitcnt lgkmcnt(3)
	v_mfma_f32_32x32x16_bf16 v[80:95], v[128:131], v[120:123], v[80:95]
	v_add_f32_e32 v144, v196, v144
	v_exp_f32_e32 v137, v145
	v_exp_f32_e32 v138, v158
	v_exp_f32_e32 v139, v159
	s_waitcnt vmcnt(0)
	v_exp_f32_e32 v140, v152
	v_exp_f32_e32 v141, v153
	v_exp_f32_e32 v142, v146
	s_waitcnt lgkmcnt(2)
	v_mfma_f32_32x32x16_bf16 v[64:79], v[132:135], v[120:123], v[64:79]
	ds_read_b128 v[128:131], v163 offset:49152
	ds_read_b128 v[132:135], v163 offset:57344
	v_exp_f32_e32 v143, v147
	s_sub_i32 s0, s26, 63
	s_waitcnt lgkmcnt(3)
	v_mfma_f32_32x32x16_bf16 v[80:95], v[248:251], v[116:119], v[80:95]
	s_waitcnt lgkmcnt(2)
	v_mfma_f32_32x32x16_bf16 v[64:79], v[252:255], v[116:119], v[64:79]
	ds_read_b128 v[248:251], v180 offset:49280
	ds_read_b128 v[252:255], v180 offset:57472
	s_waitcnt lgkmcnt(3)
	v_mfma_f32_32x32x16_bf16 v[80:95], v[128:131], v[112:115], v[80:95]
	s_waitcnt lgkmcnt(2)
	v_mfma_f32_32x32x16_bf16 v[64:79], v[132:135], v[112:115], v[64:79]
	ds_read_b128 v[128:131], v179 offset:49280
	ds_read_b128 v[132:135], v179 offset:57472
	s_waitcnt lgkmcnt(3)
	v_mfma_f32_32x32x16_bf16 v[80:95], v[248:251], v[108:111], v[80:95]
	s_waitcnt lgkmcnt(2)
	v_mfma_f32_32x32x16_bf16 v[64:79], v[252:255], v[108:111], v[64:79]
	ds_read_b128 v[248:251], v165 offset:49280
	ds_read_b128 v[252:255], v165 offset:57472
	s_waitcnt lgkmcnt(3)
	v_mfma_f32_32x32x16_bf16 v[80:95], v[128:131], v[104:107], v[80:95]
	s_waitcnt lgkmcnt(2)
	v_mfma_f32_32x32x16_bf16 v[64:79], v[132:135], v[104:107], v[64:79]
	ds_read_b128 v[128:131], v163 offset:49280
	ds_read_b128 v[132:135], v163 offset:57472
	s_waitcnt lgkmcnt(3)
	v_mfma_f32_32x32x16_bf16 v[80:95], v[248:251], v[100:103], v[80:95]
	s_waitcnt lgkmcnt(2)
	v_mfma_f32_32x32x16_bf16 v[64:79], v[252:255], v[100:103], v[64:79]
	s_waitcnt lgkmcnt(1)
	v_mfma_f32_32x32x16_bf16 v[80:95], v[128:131], v[96:99], v[80:95]
	v_exp_f32_e32 v128, v156
	v_exp_f32_e32 v129, v157
	v_exp_f32_e32 v130, v154
	v_exp_f32_e32 v131, v155
	v_add_f32_e32 v144, v128, v144
	v_add_f32_e32 v144, v129, v144
	v_add_f32_e32 v144, v130, v144
	s_waitcnt lgkmcnt(0)
	v_mfma_f32_32x32x16_bf16 v[64:79], v[132:135], v[96:99], v[64:79]
	v_exp_f32_e32 v132, v150
	v_exp_f32_e32 v133, v151
	v_exp_f32_e32 v134, v148
	v_exp_f32_e32 v135, v149
	v_add_f32_e32 v144, v131, v144
	v_add_f32_e32 v144, v132, v144
	v_add_f32_e32 v144, v133, v144
	v_add_f32_e32 v144, v134, v144
	v_add_f32_e32 v144, v135, v144
	v_add_f32_e32 v144, v136, v144
	v_add_f32_e32 v144, v137, v144
	v_add_f32_e32 v144, v138, v144
	v_add_f32_e32 v144, v139, v144
	v_add_f32_e32 v144, v140, v144
	v_add_f32_e32 v144, v141, v144
	v_add_f32_e32 v144, v142, v144
	v_add_f32_e32 v190, v143, v144
	v_mov_b32_e32 v191, v190
	s_nop 1
	v_permlane32_swap_b32_e32 v190, v191
	v_cvt_pk_bf16_f32 v144, v216, v219
	v_cvt_pk_bf16_f32 v145, v213, v217
	v_cvt_pk_bf16_f32 v146, v212, v214
	v_cvt_pk_bf16_f32 v147, v210, v211
	v_cvt_pk_bf16_f32 v148, v207, v209
	v_cvt_pk_bf16_f32 v149, v206, v208
	v_cvt_pk_bf16_f32 v150, v195, v197
	v_cvt_pk_bf16_f32 v151, v194, v196
	v_cvt_pk_bf16_f32 v152, v128, v129
	v_cvt_pk_bf16_f32 v153, v130, v131
	v_cvt_pk_bf16_f32 v154, v132, v133
	v_cvt_pk_bf16_f32 v155, v134, v135
	v_cvt_pk_bf16_f32 v156, v136, v137
	v_cvt_pk_bf16_f32 v157, v138, v139
	v_cvt_pk_bf16_f32 v158, v140, v141
	v_cvt_pk_bf16_f32 v159, v142, v143
	s_nop 0
	v_permlane32_swap_b32_e32 v144, v146
	v_permlane32_swap_b32_e32 v145, v147
	v_permlane32_swap_b32_e32 v148, v150
	v_permlane32_swap_b32_e32 v149, v151
	v_permlane32_swap_b32_e32 v152, v154
	v_permlane32_swap_b32_e32 v153, v155
	v_permlane32_swap_b32_e32 v156, v158
	v_permlane32_swap_b32_e32 v157, v159
	v_add_u32_e32 v192, s26, v160
	v_add_u32_e32 v128, 1, v192
	v_add_u32_e32 v130, 33, v192
	v_ashrrev_i32_e32 v129, 31, v128
	v_ashrrev_i32_e32 v131, 31, v130
	v_lshlrev_b64 v[136:137], 8, v[128:129]
	v_lshlrev_b64 v[138:139], 8, v[130:131]
	v_lshl_add_u64 v[128:129], v[166:167], 0, v[136:137]
	v_lshl_add_u64 v[132:133], v[166:167], 0, v[138:139]
	v_lshl_add_u64 v[136:137], v[168:169], 0, v[136:137]
	v_lshl_add_u64 v[140:141], v[168:169], 0, v[138:139]
	global_load_dwordx4 v[128:131], v[128:129], off
	s_nop 0
	global_load_dwordx4 v[132:135], v[132:133], off
	s_nop 0
	global_load_dwordx4 v[136:139], v[136:137], off
	s_nop 0
	global_load_dwordx4 v[140:143], v[140:141], off
	ds_read_b64_tr_b16 v[194:195], v173 offset:0
	ds_read_b64_tr_b16 v[196:197], v173 offset:0x800
	ds_read_b64_tr_b16 v[206:207], v173 offset:0x1000
	ds_read_b64_tr_b16 v[208:209], v173 offset:0x1800
	ds_read_b64_tr_b16 v[210:211], v173 offset:0x2000
	ds_read_b64_tr_b16 v[212:213], v173 offset:0x2800
	ds_read_b64_tr_b16 v[214:215], v173 offset:0x3000
	ds_read_b64_tr_b16 v[216:217], v173 offset:0x3800
	s_waitcnt lgkmcnt(0)
	s_nop 0
	v_mfma_f32_32x32x16_bf16 v[48:63], v[144:147], v[194:197], v[48:63]
	ds_read_b64_tr_b16 v[194:195], v173 offset:0x200
	ds_read_b64_tr_b16 v[196:197], v173 offset:0xa00
	v_mfma_f32_32x32x16_bf16 v[48:63], v[148:151], v[206:209], v[48:63]
	ds_read_b64_tr_b16 v[206:207], v173 offset:0x1200
	ds_read_b64_tr_b16 v[208:209], v173 offset:0x1a00
	v_mfma_f32_32x32x16_bf16 v[48:63], v[152:155], v[210:213], v[48:63]
	ds_read_b64_tr_b16 v[210:211], v173 offset:0x2200
	ds_read_b64_tr_b16 v[212:213], v173 offset:0x2a00
	v_mfma_f32_32x32x16_bf16 v[48:63], v[156:159], v[214:217], v[48:63]
	ds_read_b64_tr_b16 v[214:215], v173 offset:0x3200
	ds_read_b64_tr_b16 v[216:217], v173 offset:0x3a00
	s_waitcnt lgkmcnt(0)
	v_mfma_f32_32x32x16_bf16 v[32:47], v[144:147], v[194:197], v[32:47]
	ds_read_b64_tr_b16 v[194:195], v173 offset:0x400
	ds_read_b64_tr_b16 v[196:197], v173 offset:0xc00
	v_mfma_f32_32x32x16_bf16 v[32:47], v[148:151], v[206:209], v[32:47]
	ds_read_b64_tr_b16 v[206:207], v173 offset:0x1400
	ds_read_b64_tr_b16 v[208:209], v173 offset:0x1c00
	v_mfma_f32_32x32x16_bf16 v[32:47], v[152:155], v[210:213], v[32:47]
	ds_read_b64_tr_b16 v[210:211], v173 offset:0x2400
	ds_read_b64_tr_b16 v[212:213], v173 offset:0x2c00
	v_mfma_f32_32x32x16_bf16 v[32:47], v[156:159], v[214:217], v[32:47]
	ds_read_b64_tr_b16 v[214:215], v173 offset:0x3400
	ds_read_b64_tr_b16 v[216:217], v173 offset:0x3c00
	s_waitcnt lgkmcnt(0)
	v_mfma_f32_32x32x16_bf16 v[16:31], v[144:147], v[194:197], v[16:31]
	ds_read_b64_tr_b16 v[194:195], v173 offset:0x600
	ds_read_b64_tr_b16 v[196:197], v173 offset:0xe00
	v_mfma_f32_32x32x16_bf16 v[16:31], v[148:151], v[206:209], v[16:31]
	ds_read_b64_tr_b16 v[206:207], v173 offset:0x1600
	ds_read_b64_tr_b16 v[208:209], v173 offset:0x1e00
	v_mfma_f32_32x32x16_bf16 v[16:31], v[152:155], v[210:213], v[16:31]
	ds_read_b64_tr_b16 v[210:211], v173 offset:0x2600
	ds_read_b64_tr_b16 v[212:213], v173 offset:0x2e00
	v_mfma_f32_32x32x16_bf16 v[16:31], v[156:159], v[214:217], v[16:31]
	ds_read_b64_tr_b16 v[214:215], v173 offset:0x3600
	ds_read_b64_tr_b16 v[216:217], v173 offset:0x3e00
	s_waitcnt lgkmcnt(0)
	v_mfma_f32_32x32x16_bf16 v[0:15], v[144:147], v[194:197], v[0:15]
	s_cmp_le_i32 s26, s19
	s_cselect_b64 s[2:3], -1, 0
	s_cmp_gt_i32 s0, s24
	s_cselect_b64 s[0:1], -1, 0
	s_and_b64 s[0:1], s[2:3], s[0:1]
	s_and_b64 vcc, exec, s[0:1]
	v_mfma_f32_32x32x16_bf16 v[0:15], v[148:151], v[206:209], v[0:15]
	v_mfma_f32_32x32x16_bf16 v[0:15], v[152:155], v[210:213], v[0:15]
	v_mfma_f32_32x32x16_bf16 v[0:15], v[156:159], v[214:217], v[0:15]
	s_cbranch_vccnz .LBB0_195
	v_add_u32_e32 v144, 0x207b, v188
	v_cmp_gt_u32_e32 vcc, s73, v144
	v_add_u32_e32 v144, 0x5b, v188
	s_nop 0
	v_cndmask_b32_e32 v80, v202, v80, vcc
	v_cmp_lt_u32_e32 vcc, s95, v144
	v_add_u32_e32 v144, 0x7a, v188
	s_nop 0
	v_cndmask_b32_e32 v64, v202, v64, vcc
	v_cmp_lt_u32_e32 vcc, s95, v144
	v_add_u32_e32 v144, 0x5a, v188
	s_nop 0
	v_cndmask_b32_e32 v81, v202, v81, vcc
	v_cmp_lt_u32_e32 vcc, s95, v144
	v_add_u32_e32 v144, 0x79, v188
	s_nop 0
	v_cndmask_b32_e32 v65, v202, v65, vcc
	v_cmp_lt_u32_e32 vcc, s95, v144
	v_add_u32_e32 v144, 0x59, v188
	s_nop 0
	v_cndmask_b32_e32 v82, v202, v82, vcc
	v_cmp_lt_u32_e32 vcc, s95, v144
	v_add_u32_e32 v144, 0x78, v188
	s_nop 0
	v_cndmask_b32_e32 v66, v202, v66, vcc
	v_cmp_lt_u32_e32 vcc, s95, v144
	v_add_u32_e32 v144, 0x58, v188
	s_nop 0
	v_cndmask_b32_e32 v83, v202, v83, vcc
	v_cmp_lt_u32_e32 vcc, s95, v144
	v_add_u32_e32 v144, 0x73, v188
	s_nop 0
	v_cndmask_b32_e32 v67, v202, v67, vcc
	v_cmp_lt_u32_e32 vcc, s95, v144
	v_add_u32_e32 v144, 0x53, v188
	s_nop 0
	v_cndmask_b32_e32 v84, v202, v84, vcc
	v_cmp_lt_u32_e32 vcc, s95, v144
	v_add_u32_e32 v144, 0x72, v188
	s_nop 0
	v_cndmask_b32_e32 v68, v202, v68, vcc
	v_cmp_lt_u32_e32 vcc, s95, v144
	v_add_u32_e32 v144, 0x52, v188
	s_nop 0
	v_cndmask_b32_e32 v85, v202, v85, vcc
	v_cmp_lt_u32_e32 vcc, s95, v144
	v_add_u32_e32 v144, 0x71, v188
	s_nop 0
	v_cndmask_b32_e32 v69, v202, v69, vcc
	v_cmp_lt_u32_e32 vcc, s95, v144
	v_add_u32_e32 v144, 0x51, v188
	s_nop 0
	v_cndmask_b32_e32 v86, v202, v86, vcc
	v_cmp_lt_u32_e32 vcc, s95, v144
	v_add_u32_e32 v144, 0x70, v188
	s_nop 0
	v_cndmask_b32_e32 v70, v202, v70, vcc
	v_cmp_lt_u32_e32 vcc, s95, v144
	v_add_u32_e32 v144, 0x50, v188
	s_nop 0
	v_cndmask_b32_e32 v87, v202, v87, vcc
	v_cmp_lt_u32_e32 vcc, s95, v144
	v_add_u32_e32 v144, 0x6b, v188
	s_nop 0
	v_cndmask_b32_e32 v71, v202, v71, vcc
	v_cmp_lt_u32_e32 vcc, s95, v144
	v_add_u32_e32 v144, 0x4b, v188
	s_nop 0
	v_cndmask_b32_e32 v88, v202, v88, vcc
	v_cmp_lt_u32_e32 vcc, s95, v144
	v_add_u32_e32 v144, 0x6a, v188
	s_nop 0
	v_cndmask_b32_e32 v72, v202, v72, vcc
	v_cmp_lt_u32_e32 vcc, s95, v144
	v_add_u32_e32 v144, 0x4a, v188
	s_nop 0
	v_cndmask_b32_e32 v89, v202, v89, vcc
	v_cmp_lt_u32_e32 vcc, s95, v144
	v_add_u32_e32 v144, 0x69, v188
	s_nop 0
	v_cndmask_b32_e32 v73, v202, v73, vcc
	v_cmp_lt_u32_e32 vcc, s95, v144
	v_add_u32_e32 v144, 0x49, v188
	s_nop 0
	v_cndmask_b32_e32 v90, v202, v90, vcc
	v_cmp_lt_u32_e32 vcc, s95, v144
	v_add_u32_e32 v144, 0x68, v188
	s_nop 0
	v_cndmask_b32_e32 v74, v202, v74, vcc
	v_cmp_lt_u32_e32 vcc, s95, v144
	v_add_u32_e32 v144, 0x48, v188
	s_nop 0
	v_cndmask_b32_e32 v91, v202, v91, vcc
	v_cmp_lt_u32_e32 vcc, s95, v144
	v_add_u32_e32 v144, 0x63, v188
	s_nop 0
	v_cndmask_b32_e32 v75, v202, v75, vcc
	v_cmp_lt_u32_e32 vcc, s95, v144
	v_add_u32_e32 v144, 0x43, v188
	s_nop 0
	v_cndmask_b32_e32 v92, v202, v92, vcc
	v_cmp_lt_u32_e32 vcc, s95, v144
	v_add_u32_e32 v144, 0x62, v188
	s_nop 0
	v_cndmask_b32_e32 v76, v202, v76, vcc
	v_cmp_lt_u32_e32 vcc, s95, v144
	v_add_u32_e32 v144, 0x42, v188
	s_nop 0
	v_cndmask_b32_e32 v93, v202, v93, vcc
	v_cmp_lt_u32_e32 vcc, s95, v144
	v_add_u32_e32 v144, 0x61, v188
	s_nop 0
	v_cndmask_b32_e32 v77, v202, v77, vcc
	v_cmp_lt_u32_e32 vcc, s95, v144
	v_add_u32_e32 v144, 0x41, v188
	s_nop 0
	v_cndmask_b32_e32 v94, v202, v94, vcc
	v_cmp_lt_u32_e32 vcc, s95, v144
	v_add_u32_e32 v144, 0x60, v188
	s_nop 0
	v_cndmask_b32_e32 v78, v202, v78, vcc
	v_cmp_lt_u32_e32 vcc, s95, v144
	v_add_u32_e32 v144, 64, v188
	s_nop 0
	v_cndmask_b32_e32 v95, v202, v95, vcc
	v_cmp_lt_u32_e32 vcc, s95, v144
	s_nop 1
	v_cndmask_b32_e32 v79, v202, v79, vcc

.LBB0_199:
	v_cndmask_b32_e64 v186, v144, v186, s[0:1]
	v_mul_f32_e32 v194, 0xbe0293ee, v186
	v_fmamk_f32 v80, v80, 0x3e0293ee, v194
	v_fmamk_f32 v81, v81, 0x3e0293ee, v194
	v_fmamk_f32 v82, v82, 0x3e0293ee, v194
	v_fmamk_f32 v83, v83, 0x3e0293ee, v194
	v_fmamk_f32 v84, v84, 0x3e0293ee, v194
	v_fmamk_f32 v85, v85, 0x3e0293ee, v194
	v_fmamk_f32 v86, v86, 0x3e0293ee, v194
	v_fmamk_f32 v87, v87, 0x3e0293ee, v194
	v_fmamk_f32 v88, v88, 0x3e0293ee, v194
	v_fmamk_f32 v89, v89, 0x3e0293ee, v194
	v_fmamk_f32 v90, v90, 0x3e0293ee, v194
	v_fmamk_f32 v91, v91, 0x3e0293ee, v194
	v_fmamk_f32 v92, v92, 0x3e0293ee, v194
	v_fmamk_f32 v93, v93, 0x3e0293ee, v194
	v_fmamk_f32 v94, v94, 0x3e0293ee, v194
	v_fmamk_f32 v95, v95, 0x3e0293ee, v194
	v_exp_f32_e32 v144, v80
	v_exp_f32_e32 v159, v81
	v_exp_f32_e32 v145, v82
	v_exp_f32_e32 v158, v83
	v_exp_f32_e32 v146, v84
	v_exp_f32_e32 v157, v85
	v_exp_f32_e32 v147, v86
	v_exp_f32_e32 v156, v87
	v_exp_f32_e32 v148, v88
	v_exp_f32_e32 v155, v89
	v_exp_f32_e32 v149, v90
	v_exp_f32_e32 v154, v91
	v_exp_f32_e32 v150, v92
	v_exp_f32_e32 v153, v93
	v_exp_f32_e32 v151, v94
	v_exp_f32_e32 v152, v95
	v_fmamk_f32 v215, v68, 0x3e0293ee, v194
	v_fmamk_f32 v211, v64, 0x3e0293ee, v194
	v_fmamk_f32 v212, v65, 0x3e0293ee, v194
	v_fmamk_f32 v213, v66, 0x3e0293ee, v194
	v_fmamk_f32 v214, v67, 0x3e0293ee, v194
	v_fmamk_f32 v196, v69, 0x3e0293ee, v194
	v_fmamk_f32 v197, v70, 0x3e0293ee, v194
	v_fmamk_f32 v206, v71, 0x3e0293ee, v194
	v_fmamk_f32 v207, v72, 0x3e0293ee, v194
	v_fmamk_f32 v208, v73, 0x3e0293ee, v194
	v_fmamk_f32 v209, v74, 0x3e0293ee, v194
	v_fmamk_f32 v210, v75, 0x3e0293ee, v194
	v_fmamk_f32 v195, v76, 0x3e0293ee, v194
	v_fmamk_f32 v216, v77, 0x3e0293ee, v194
	v_fmamk_f32 v217, v78, 0x3e0293ee, v194
	v_fmac_f32_e32 v194, 0x3e0293ee, v79
	s_waitcnt lgkmcnt(0)
	s_barrier
	ds_read_b128 v[64:67], v180 offset:32768
	ds_read_b128 v[68:71], v180 offset:40960
	ds_read_b128 v[218:221], v179 offset:32768
	ds_read_b128 v[222:225], v179 offset:40960
	ds_read_b128 v[248:251], v165 offset:32768
	ds_read_b128 v[252:255], v165 offset:40960
	v_exp_f32_e32 v211, v211
	v_exp_f32_e32 v212, v212
	s_waitcnt lgkmcnt(5)
	v_mfma_f32_32x32x16_bf16 v[80:95], v[64:67], v[124:127], 0
	v_exp_f32_e32 v213, v213
	v_exp_f32_e32 v214, v214
	v_exp_f32_e32 v196, v196
	v_exp_f32_e32 v197, v197
	v_exp_f32_e32 v206, v206
	v_exp_f32_e32 v207, v207
	v_exp_f32_e32 v208, v208
	s_waitcnt lgkmcnt(4)
	v_mfma_f32_32x32x16_bf16 v[64:79], v[68:71], v[124:127], 0
	v_exp_f32_e32 v209, v209
	v_exp_f32_e32 v210, v210
	v_exp_f32_e32 v195, v195
	v_exp_f32_e32 v216, v216
	v_exp_f32_e32 v217, v217
	v_exp_f32_e32 v194, v194
	s_waitcnt lgkmcnt(3)
	v_mfma_f32_32x32x16_bf16 v[80:95], v[218:221], v[120:123], v[80:95]
	s_waitcnt lgkmcnt(2)
	v_mfma_f32_32x32x16_bf16 v[64:79], v[222:225], v[120:123], v[64:79]
	ds_read_b128 v[218:221], v163 offset:32768
	ds_read_b128 v[222:225], v163 offset:40960
	s_waitcnt lgkmcnt(3)
	v_mfma_f32_32x32x16_bf16 v[80:95], v[248:251], v[116:119], v[80:95]
	s_waitcnt lgkmcnt(2)
	v_mfma_f32_32x32x16_bf16 v[64:79], v[252:255], v[116:119], v[64:79]
	ds_read_b128 v[248:251], v180 offset:32896
	ds_read_b128 v[252:255], v180 offset:41088
	s_waitcnt lgkmcnt(3)
	v_mfma_f32_32x32x16_bf16 v[80:95], v[218:221], v[112:115], v[80:95]
	s_waitcnt lgkmcnt(2)
	v_mfma_f32_32x32x16_bf16 v[64:79], v[222:225], v[112:115], v[64:79]
	ds_read_b128 v[218:221], v179 offset:32896
	ds_read_b128 v[222:225], v179 offset:41088
	s_waitcnt lgkmcnt(3)
	v_mfma_f32_32x32x16_bf16 v[80:95], v[248:251], v[108:111], v[80:95]
	s_waitcnt lgkmcnt(2)
	v_mfma_f32_32x32x16_bf16 v[64:79], v[252:255], v[108:111], v[64:79]
	ds_read_b128 v[248:251], v165 offset:32896
	ds_read_b128 v[252:255], v165 offset:41088
	s_waitcnt lgkmcnt(3)
	v_mfma_f32_32x32x16_bf16 v[80:95], v[218:221], v[104:107], v[80:95]
	s_waitcnt lgkmcnt(2)
	v_mfma_f32_32x32x16_bf16 v[64:79], v[222:225], v[104:107], v[64:79]
	ds_read_b128 v[218:221], v163 offset:32896
	ds_read_b128 v[222:225], v163 offset:41088
	s_waitcnt lgkmcnt(3)
	v_mfma_f32_32x32x16_bf16 v[80:95], v[248:251], v[100:103], v[80:95]
	s_waitcnt lgkmcnt(2)
	v_mfma_f32_32x32x16_bf16 v[64:79], v[252:255], v[100:103], v[64:79]
	s_waitcnt lgkmcnt(1)
	v_mfma_f32_32x32x16_bf16 v[80:95], v[218:221], v[96:99], v[80:95]
	v_exp_f32_e32 v219, v215
	v_add_f32_e32 v215, 0, v144
	v_add_f32_e32 v215, v159, v215
	v_add_f32_e32 v215, v145, v215
	v_add_f32_e32 v215, v158, v215
	v_add_f32_e32 v215, v146, v215
	v_add_f32_e32 v215, v157, v215
	v_add_f32_e32 v215, v147, v215
	v_add_f32_e32 v215, v156, v215
	v_add_f32_e32 v215, v148, v215
	v_add_f32_e32 v215, v155, v215
	v_add_f32_e32 v215, v149, v215
	v_add_f32_e32 v215, v154, v215
	v_add_f32_e32 v215, v150, v215
	v_add_f32_e32 v215, v153, v215
	v_add_f32_e32 v215, v151, v215
	v_add_f32_e32 v215, v152, v215
	v_add_f32_e32 v215, v211, v215
	v_add_f32_e32 v215, v212, v215
	v_add_f32_e32 v215, v213, v215
	v_add_f32_e32 v215, v214, v215
	v_add_f32_e32 v215, v219, v215
	v_add_f32_e32 v215, v196, v215
	v_add_f32_e32 v215, v197, v215
	v_add_f32_e32 v215, v206, v215
	v_add_f32_e32 v215, v207, v215
	v_add_f32_e32 v215, v208, v215
	s_waitcnt lgkmcnt(0)
	v_mfma_f32_32x32x16_bf16 v[64:79], v[222:225], v[96:99], v[64:79]
	v_add_f32_e32 v215, v209, v215
	v_add_f32_e32 v215, v210, v215
	v_add_f32_e32 v215, v195, v215
	v_add_f32_e32 v215, v216, v215
	v_add_f32_e32 v215, v217, v215
	v_add_f32_e32 v215, v194, v215
	v_mov_b32_e32 v218, v215
	v_cvt_pk_bf16_f32 v144, v144, v159
	v_cvt_pk_bf16_f32 v145, v145, v158
	v_cvt_pk_bf16_f32 v146, v146, v157
	v_cvt_pk_bf16_f32 v147, v147, v156
	v_cvt_pk_bf16_f32 v148, v148, v155
	v_cvt_pk_bf16_f32 v149, v149, v154
	v_cvt_pk_bf16_f32 v150, v150, v153
	v_cvt_pk_bf16_f32 v151, v151, v152
	v_cvt_pk_bf16_f32 v152, v211, v212
	v_cvt_pk_bf16_f32 v153, v213, v214
	v_cvt_pk_bf16_f32 v154, v219, v196
	v_cvt_pk_bf16_f32 v155, v197, v206
	v_cvt_pk_bf16_f32 v156, v207, v208
	v_cvt_pk_bf16_f32 v157, v209, v210
	v_cvt_pk_bf16_f32 v158, v195, v216
	v_cvt_pk_bf16_f32 v159, v217, v194
	s_nop 1
	v_permlane32_swap_b32_e32 v215, v218
	v_permlane32_swap_b32_e32 v144, v146
	v_permlane32_swap_b32_e32 v145, v147
	v_permlane32_swap_b32_e32 v148, v150
	v_permlane32_swap_b32_e32 v149, v151
	v_permlane32_swap_b32_e32 v152, v154
	v_permlane32_swap_b32_e32 v153, v155
	v_permlane32_swap_b32_e32 v156, v158
	v_permlane32_swap_b32_e32 v157, v159
	s_add_i32 s0, s25, 1
	s_cmp_lt_u32 s0, s23
	s_cselect_b64 s[2:3], -1, 0
	s_cmp_ge_u32 s0, s23
	s_cbranch_scc1 .LBB0_201
	v_add_u32_e32 v128, 0x41, v192
	v_add_u32_e32 v130, 0x61, v192
	v_ashrrev_i32_e32 v129, 31, v128
	v_ashrrev_i32_e32 v131, 31, v130
	v_lshlrev_b64 v[136:137], 8, v[128:129]
	v_lshlrev_b64 v[138:139], 8, v[130:131]
	v_lshl_add_u64 v[128:129], v[166:167], 0, v[136:137]
	v_lshl_add_u64 v[132:133], v[166:167], 0, v[138:139]
	v_lshl_add_u64 v[136:137], v[168:169], 0, v[136:137]
	v_lshl_add_u64 v[140:141], v[168:169], 0, v[138:139]
	global_load_dwordx4 v[128:131], v[128:129], off
	s_nop 0
	global_load_dwordx4 v[132:135], v[132:133], off
	s_nop 0
	global_load_dwordx4 v[136:139], v[136:137], off
	s_nop 0
	global_load_dwordx4 v[140:143], v[140:141], off

.LBB0_347:
	s_setprio 0
	v_readlane_b32 s6, v247, 5
	v_readlane_b32 s4, v247, 4
	v_readlane_b32 s19, v247, 6
	s_waitcnt vmcnt(0)
	s_barrier
	s_mov_b64 s[0:1], exec
	v_readlane_b32 s2, v247, 2
	v_readlane_b32 s3, v247, 3
	s_and_b64 s[2:3], s[0:1], s[2:3]
	s_mov_b64 exec, s[2:3]
	s_cbranch_execz .LBB0_384
	s_mov_b64 s[2:3], exec
	v_mbcnt_lo_u32_b32 v0, s2, 0
	v_mbcnt_hi_u32_b32 v0, s3, v0
	s_lshl_b32 s18, s4, 6
	v_cmp_eq_u32_e32 vcc, 0, v0
	s_waitcnt vmcnt(0) expcnt(0) lgkmcnt(0)
	s_and_saveexec_b64 s[4:5], vcc
	s_cbranch_execz .LBB0_350
	s_add_i32 s64, s18, 0x500
	s_lshl_b64 s[8:9], s[64:65], 2
	v_readlane_b32 s10, v247, 0
	v_readlane_b32 s11, v247, 1
	s_add_u32 s8, s10, s8
	s_addc_u32 s9, s11, s9
	s_bcnt1_i32_b64 s2, s[2:3]
	v_mov_b32_e32 v1, s2
	global_atomic_add v1, v185, v1, s[8:9] sc0

.LBB0_429:
	s_or_b64 exec, exec, s[2:3]
	s_add_i32 s2, s10, 0x80
	s_ashr_i32 s3, s2, 31
	s_ashr_i32 s13, s0, 31
	s_mov_b32 s12, s0
	s_ashr_i32 s11, s10, 31
	s_lshl_b64 s[2:3], s[2:3], 12
	s_lshl_b64 s[8:9], s[12:13], 12
	s_lshl_b64 s[14:15], s[10:11], 12
	s_add_u32 s8, s38, s8
	s_addc_u32 s9, s39, s9
	s_add_u32 s14, s38, s14
	s_addc_u32 s15, s39, s15
	s_add_u32 s16, s38, s2
	v_mov_b32_e32 v0, 0
	s_barrier
	s_barrier
	s_addc_u32 s17, s39, s3
	s_mov_b32 s1, -2
	v_mov_b32_e32 v1, v0
	v_mov_b32_e32 v2, v0
	v_mov_b32_e32 v3, v0
	v_mov_b32_e32 v4, v0
	v_mov_b32_e32 v5, v0
	v_mov_b32_e32 v6, v0
	v_mov_b32_e32 v7, v0
	v_mov_b32_e32 v8, v0
	v_mov_b32_e32 v9, v0
	v_mov_b32_e32 v10, v0
	v_mov_b32_e32 v11, v0
	v_mov_b32_e32 v12, v0
	v_mov_b32_e32 v13, v0
	v_mov_b32_e32 v14, v0
	v_mov_b32_e32 v15, v0
	v_mov_b32_e32 v16, v0
	v_mov_b32_e32 v17, v0
	v_mov_b32_e32 v18, v0
	v_mov_b32_e32 v19, v0
	v_mov_b32_e32 v20, v0
	v_mov_b32_e32 v21, v0
	v_mov_b32_e32 v22, v0
	v_mov_b32_e32 v23, v0
	v_mov_b32_e32 v24, v0
	v_mov_b32_e32 v25, v0
	v_mov_b32_e32 v26, v0
	v_mov_b32_e32 v27, v0
	v_mov_b32_e32 v28, v0
	v_mov_b32_e32 v29, v0
	v_mov_b32_e32 v30, v0
	v_mov_b32_e32 v31, v0
	v_mov_b32_e32 v32, v0
	v_mov_b32_e32 v33, v0
	v_mov_b32_e32 v34, v0
	v_mov_b32_e32 v35, v0
	v_mov_b32_e32 v36, v0
	v_mov_b32_e32 v37, v0
	v_mov_b32_e32 v38, v0
	v_mov_b32_e32 v39, v0
	v_mov_b32_e32 v40, v0
	v_mov_b32_e32 v41, v0
	v_mov_b32_e32 v42, v0
	v_mov_b32_e32 v43, v0
	v_mov_b32_e32 v44, v0
	v_mov_b32_e32 v45, v0
	v_mov_b32_e32 v46, v0
	v_mov_b32_e32 v47, v0
	v_mov_b32_e32 v48, v0
	v_mov_b32_e32 v49, v0
	v_mov_b32_e32 v50, v0
	v_mov_b32_e32 v51, v0
	v_mov_b32_e32 v52, v0
	v_mov_b32_e32 v53, v0
	v_mov_b32_e32 v54, v0
	v_mov_b32_e32 v55, v0
	v_mov_b32_e32 v56, v0
	v_mov_b32_e32 v57, v0
	v_mov_b32_e32 v58, v0
	v_mov_b32_e32 v59, v0
	v_mov_b32_e32 v60, v0
	v_mov_b32_e32 v61, v0
	v_mov_b32_e32 v62, v0
	v_mov_b32_e32 v63, v0
	v_mov_b32_e32 v64, v0
	v_mov_b32_e32 v65, v0
	v_mov_b32_e32 v66, v0
	v_mov_b32_e32 v67, v0
	v_mov_b32_e32 v68, v0
	v_mov_b32_e32 v69, v0
	v_mov_b32_e32 v70, v0
	v_mov_b32_e32 v71, v0
	v_mov_b32_e32 v72, v0
	v_mov_b32_e32 v73, v0
	v_mov_b32_e32 v74, v0
	v_mov_b32_e32 v75, v0
	v_mov_b32_e32 v76, v0
	v_mov_b32_e32 v77, v0
	v_mov_b32_e32 v78, v0
	v_mov_b32_e32 v79, v0
	v_mov_b32_e32 v80, v0
	v_mov_b32_e32 v81, v0
	v_mov_b32_e32 v82, v0
	v_mov_b32_e32 v83, v0
	v_mov_b32_e32 v84, v0
	v_mov_b32_e32 v85, v0
	v_mov_b32_e32 v86, v0
	v_mov_b32_e32 v87, v0
	v_mov_b32_e32 v88, v0
	v_mov_b32_e32 v89, v0
	v_mov_b32_e32 v90, v0
	v_mov_b32_e32 v91, v0
	v_mov_b32_e32 v92, v0
	v_mov_b32_e32 v93, v0
	v_mov_b32_e32 v94, v0
	v_mov_b32_e32 v95, v0
	v_mov_b32_e32 v96, v0
	v_mov_b32_e32 v97, v0
	v_mov_b32_e32 v98, v0
	v_mov_b32_e32 v99, v0
	v_mov_b32_e32 v100, v0
	v_mov_b32_e32 v101, v0
	v_mov_b32_e32 v102, v0
	v_mov_b32_e32 v103, v0
	v_mov_b32_e32 v104, v0
	v_mov_b32_e32 v105, v0
	v_mov_b32_e32 v106, v0
	v_mov_b32_e32 v107, v0
	v_mov_b32_e32 v108, v0
	v_mov_b32_e32 v109, v0
	v_mov_b32_e32 v110, v0
	v_mov_b32_e32 v111, v0
	v_mov_b32_e32 v112, v0
	v_mov_b32_e32 v113, v0
	v_mov_b32_e32 v114, v0
	v_mov_b32_e32 v115, v0
	v_mov_b32_e32 v116, v0
	v_mov_b32_e32 v117, v0
	v_mov_b32_e32 v118, v0
	v_mov_b32_e32 v119, v0
	v_mov_b32_e32 v120, v0
	v_mov_b32_e32 v121, v0
	v_mov_b32_e32 v122, v0
	v_mov_b32_e32 v123, v0
	v_mov_b32_e32 v124, v0
	v_mov_b32_e32 v125, v0
	v_mov_b32_e32 v126, v0
	v_mov_b32_e32 v127, v0
	s_mov_b64 s[22:23], 0x14000100
	s_mov_b64 s[24:25], 0x14040100
	s_mov_b64 s[76:77], 0x14000180
	.p2align 6

.LBB0_442:
	s_or_b64 exec, exec, s[8:9]
	s_add_i32 s8, s0, 0x80
	s_ashr_i32 s9, s8, 31
	s_ashr_i32 s3, s2, 31
	s_lshl_b64 s[8:9], s[8:9], 12
	s_lshl_b64 s[10:11], s[2:3], 12
	s_add_u32 s10, s38, s10
	s_addc_u32 s11, s39, s11
	s_ashr_i32 s1, s0, 31
	s_lshl_b64 s[12:13], s[0:1], 12
	s_add_u32 s12, s38, s12
	s_addc_u32 s13, s39, s13
	s_add_u32 s14, s38, s8
	v_mov_b32_e32 v0, 0
	s_addc_u32 s15, s39, s9
	s_mov_b32 s17, -2
	v_mov_b32_e32 v1, v0
	v_mov_b32_e32 v2, v0
	v_mov_b32_e32 v3, v0
	v_mov_b32_e32 v4, v0
	v_mov_b32_e32 v5, v0
	v_mov_b32_e32 v6, v0
	v_mov_b32_e32 v7, v0
	v_mov_b32_e32 v8, v0
	v_mov_b32_e32 v9, v0
	v_mov_b32_e32 v10, v0
	v_mov_b32_e32 v11, v0
	v_mov_b32_e32 v12, v0
	v_mov_b32_e32 v13, v0
	v_mov_b32_e32 v14, v0
	v_mov_b32_e32 v15, v0
	v_mov_b32_e32 v16, v0
	v_mov_b32_e32 v17, v0
	v_mov_b32_e32 v18, v0
	v_mov_b32_e32 v19, v0
	v_mov_b32_e32 v20, v0
	v_mov_b32_e32 v21, v0
	v_mov_b32_e32 v22, v0
	v_mov_b32_e32 v23, v0
	v_mov_b32_e32 v24, v0
	v_mov_b32_e32 v25, v0
	v_mov_b32_e32 v26, v0
	v_mov_b32_e32 v27, v0
	v_mov_b32_e32 v28, v0
	v_mov_b32_e32 v29, v0
	v_mov_b32_e32 v30, v0
	v_mov_b32_e32 v31, v0
	v_mov_b32_e32 v32, v0
	v_mov_b32_e32 v33, v0
	v_mov_b32_e32 v34, v0
	v_mov_b32_e32 v35, v0
	v_mov_b32_e32 v36, v0
	v_mov_b32_e32 v37, v0
	v_mov_b32_e32 v38, v0
	v_mov_b32_e32 v39, v0
	v_mov_b32_e32 v40, v0
	v_mov_b32_e32 v41, v0
	v_mov_b32_e32 v42, v0
	v_mov_b32_e32 v43, v0
	v_mov_b32_e32 v44, v0
	v_mov_b32_e32 v45, v0
	v_mov_b32_e32 v46, v0
	v_mov_b32_e32 v47, v0
	v_mov_b32_e32 v48, v0
	v_mov_b32_e32 v49, v0
	v_mov_b32_e32 v50, v0
	v_mov_b32_e32 v51, v0
	v_mov_b32_e32 v52, v0
	v_mov_b32_e32 v53, v0
	v_mov_b32_e32 v54, v0
	v_mov_b32_e32 v55, v0
	v_mov_b32_e32 v56, v0
	v_mov_b32_e32 v57, v0
	v_mov_b32_e32 v58, v0
	v_mov_b32_e32 v59, v0
	v_mov_b32_e32 v60, v0
	v_mov_b32_e32 v61, v0
	v_mov_b32_e32 v62, v0
	v_mov_b32_e32 v63, v0
	v_mov_b32_e32 v64, v0
	v_mov_b32_e32 v65, v0
	v_mov_b32_e32 v66, v0
	v_mov_b32_e32 v67, v0
	v_mov_b32_e32 v68, v0
	v_mov_b32_e32 v69, v0
	v_mov_b32_e32 v70, v0
	v_mov_b32_e32 v71, v0
	v_mov_b32_e32 v72, v0
	v_mov_b32_e32 v73, v0
	v_mov_b32_e32 v74, v0
	v_mov_b32_e32 v75, v0
	v_mov_b32_e32 v76, v0
	v_mov_b32_e32 v77, v0
	v_mov_b32_e32 v78, v0
	v_mov_b32_e32 v79, v0
	v_mov_b32_e32 v80, v0
	v_mov_b32_e32 v81, v0
	v_mov_b32_e32 v82, v0
	v_mov_b32_e32 v83, v0
	v_mov_b32_e32 v84, v0
	v_mov_b32_e32 v85, v0
	v_mov_b32_e32 v86, v0
	v_mov_b32_e32 v87, v0
	v_mov_b32_e32 v88, v0
	v_mov_b32_e32 v89, v0
	v_mov_b32_e32 v90, v0
	v_mov_b32_e32 v91, v0
	v_mov_b32_e32 v92, v0
	v_mov_b32_e32 v93, v0
	v_mov_b32_e32 v94, v0
	v_mov_b32_e32 v95, v0
	v_mov_b32_e32 v96, v0
	v_mov_b32_e32 v97, v0
	v_mov_b32_e32 v98, v0
	v_mov_b32_e32 v99, v0
	v_mov_b32_e32 v100, v0
	v_mov_b32_e32 v101, v0
	v_mov_b32_e32 v102, v0
	v_mov_b32_e32 v103, v0
	v_mov_b32_e32 v104, v0
	v_mov_b32_e32 v105, v0
	v_mov_b32_e32 v106, v0
	v_mov_b32_e32 v107, v0
	v_mov_b32_e32 v108, v0
	v_mov_b32_e32 v109, v0
	v_mov_b32_e32 v110, v0
	v_mov_b32_e32 v111, v0
	v_mov_b32_e32 v112, v0
	v_mov_b32_e32 v113, v0
	v_mov_b32_e32 v114, v0
	v_mov_b32_e32 v115, v0
	v_mov_b32_e32 v116, v0
	v_mov_b32_e32 v117, v0
	v_mov_b32_e32 v118, v0
	v_mov_b32_e32 v119, v0
	v_mov_b32_e32 v120, v0
	v_mov_b32_e32 v121, v0
	v_mov_b32_e32 v122, v0
	v_mov_b32_e32 v123, v0
	v_mov_b32_e32 v124, v0
	v_mov_b32_e32 v125, v0
	v_mov_b32_e32 v126, v0
	v_mov_b32_e32 v127, v0
	s_barrier
	s_barrier
	.p2align 6

.LBB0_489:
	s_lshl_b32 s10, s87, 5
	s_add_i32 s13, s10, 0
	s_add_i32 s14, s13, 0x10000
	v_mov_b32_e32 v72, s14
	s_waitcnt lgkmcnt(0)
	s_barrier
	ds_read_b128 v[64:67], v72
	ds_read_b128 v[68:71], v72 offset:16
	s_add_i32 s12, s80, s78
	v_add_u32_e32 v217, 64, v217
	s_cmp_eq_u32 s12, 0
	s_cselect_b64 s[10:11], -1, 0
	s_add_i32 s75, s75, -1
	s_add_i32 s81, s81, 1
	s_waitcnt lgkmcnt(0)
	v_add3_u32 v64, v64, v65, v66
	v_add3_u32 v68, v67, v68, v69
	v_add3_u32 v64, v64, v70, v71
	v_add_u32_e32 v64, v64, v68
	v_cmp_eq_u32_e32 vcc, 8, v64
	s_or_b64 s[10:11], s[10:11], vcc
	s_add_u32 s78, s78, 0xffffc000
	s_addc_u32 s79, s79, -1
	s_sub_i32 s74, s74, 64
	s_and_b64 s[10:11], exec, s[10:11]
	s_or_b64 s[2:3], s[10:11], s[2:3]
	s_andn2_b64 exec, exec, s[2:3]
	s_cbranch_execz .LBB0_506
	.p2align 6

.LBB0_492:
	s_xor_b64 s[0:1], s[0:1], -1
	s_and_b32 s87, s81, 1
	s_andn2_b64 vcc, exec, s[0:1]
	s_mov_b64 s[0:1], -1
	s_cbranch_vccnz .LBB0_499
	s_cmp_ge_i32 s74, s86
	s_mov_b64 s[0:1], 0
	s_cbranch_scc1 .LBB0_499
	s_mov_b32 s76, s66
	s_mov_b64 s[82:83], s[62:63]
	s_mov_b64 s[0:1], -1
	s_cmp_lg_u32 s87, 0
	v_cmp_lt_i32_e32 vcc, 0, v217
	v_cmp_lt_i32_e64 s[22:23], 32, v217
	v_cmp_lt_i32_e64 s[10:11], 1, v217
	v_cmp_lt_i32_e64 s[20:21], 33, v217
	v_cmp_lt_i32_e64 s[12:13], 2, v217
	v_cmp_lt_i32_e64 s[18:19], 34, v217
	v_cmp_lt_i32_e64 s[14:15], 3, v217
	v_cmp_lt_i32_e64 s[16:17], 35, v217
	v_cmp_lt_i32_e64 s[72:73], 40, v217
	v_cmp_lt_i32_e64 s[70:71], 41, v217
	v_cmp_lt_i32_e64 s[68:69], 42, v217
	v_cmp_lt_i32_e64 s[66:67], 43, v217
	v_cmp_lt_i32_e64 s[62:63], 50, v217
	v_cmp_lt_i32_e64 s[64:65], 48, v217
	v_cmp_lt_i32_e64 s[58:59], 51, v217
	v_cmp_lt_i32_e64 s[60:61], 49, v217
	v_cmp_lt_i32_e64 s[54:55], 58, v217
	v_cmp_lt_i32_e64 s[56:57], 56, v217
	v_cmp_lt_i32_e64 s[50:51], 59, v217
	v_cmp_lt_i32_e64 s[52:53], 57, v217
	v_add_f32_e32 v218, 0, v195
	v_cmp_lt_i32_e64 s[48:49], 8, v217
	v_cmp_lt_i32_e64 s[46:47], 9, v217
	v_cmp_lt_i32_e64 s[44:45], 10, v217
	v_cmp_lt_i32_e64 s[42:43], 11, v217
	v_cmp_lt_i32_e64 s[38:39], 18, v217
	v_cmp_lt_i32_e64 s[40:41], 16, v217
	v_cmp_lt_i32_e64 s[34:35], 19, v217
	v_cmp_lt_i32_e64 s[36:37], 17, v217
	v_cmp_lt_i32_e64 s[28:29], 26, v217
	v_cmp_lt_i32_e64 s[30:31], 24, v217
	v_cmp_lt_i32_e64 s[24:25], 27, v217
	v_cmp_lt_i32_e64 s[26:27], 25, v217
	s_cbranch_scc0 .LBB0_496
	ds_read_b128 v[64:67], v213 offset:49152
	ds_read_b128 v[80:83], v213 offset:57344
	ds_read_b128 v[96:99], v214 offset:49152
	ds_read_b128 v[100:103], v214 offset:57344
	s_waitcnt lgkmcnt(3)
	v_mfma_f32_32x32x16_bf16 v[64:79], v[64:67], v[128:131], 0
	s_waitcnt lgkmcnt(2)
	v_mfma_f32_32x32x16_bf16 v[80:95], v[80:83], v[128:131], 0
	s_waitcnt lgkmcnt(0)
	v_mfma_f32_32x32x16_bf16 v[80:95], v[100:103], v[132:135], v[80:95]
	v_mfma_f32_32x32x16_bf16 v[64:79], v[96:99], v[132:135], v[64:79]
	ds_read_b128 v[96:99], v215 offset:49152
	ds_read_b128 v[100:103], v215 offset:57344
	s_waitcnt lgkmcnt(0)
	v_mfma_f32_32x32x16_bf16 v[80:95], v[100:103], v[136:139], v[80:95]
	v_mfma_f32_32x32x16_bf16 v[64:79], v[96:99], v[136:139], v[64:79]
	ds_read_b128 v[96:99], v216 offset:49152
	ds_read_b128 v[100:103], v216 offset:57344
	s_waitcnt lgkmcnt(0)
	v_mfma_f32_32x32x16_bf16 v[80:95], v[100:103], v[140:143], v[80:95]
	v_mfma_f32_32x32x16_bf16 v[64:79], v[96:99], v[140:143], v[64:79]
	ds_read_b128 v[96:99], v213 offset:49280
	ds_read_b128 v[100:103], v213 offset:57472
	s_waitcnt lgkmcnt(0)
	v_mfma_f32_32x32x16_bf16 v[80:95], v[100:103], v[144:147], v[80:95]
	v_mfma_f32_32x32x16_bf16 v[64:79], v[96:99], v[144:147], v[64:79]
	ds_read_b128 v[96:99], v214 offset:49280
	ds_read_b128 v[100:103], v214 offset:57472
	s_waitcnt lgkmcnt(0)
	v_mfma_f32_32x32x16_bf16 v[80:95], v[100:103], v[148:151], v[80:95]
	v_mfma_f32_32x32x16_bf16 v[64:79], v[96:99], v[148:151], v[64:79]
	ds_read_b128 v[96:99], v215 offset:49280
	ds_read_b128 v[100:103], v215 offset:57472
	s_waitcnt lgkmcnt(0)
	v_mfma_f32_32x32x16_bf16 v[80:95], v[100:103], v[152:155], v[80:95]
	v_mfma_f32_32x32x16_bf16 v[64:79], v[96:99], v[152:155], v[64:79]
	ds_read_b128 v[96:99], v216 offset:49280
	ds_read_b128 v[100:103], v216 offset:57472
	s_waitcnt lgkmcnt(0)
	v_mfma_f32_32x32x16_bf16 v[80:95], v[100:103], v[156:159], v[80:95]
	v_mfma_f32_32x32x16_bf16 v[64:79], v[96:99], v[156:159], v[64:79]
	s_nop 10
	v_mul_f32_e32 v97, 0x3db504f3, v80
	v_mul_f32_e32 v81, 0x3db504f3, v81
	v_mul_f32_e64 v80, |v97|, s91
	v_max_f32_e32 v96, 0, v97
	v_min_f32_e32 v112, 0, v97
	v_mul_f32_e64 v97, |v81|, s91
	v_max_f32_e32 v100, 0, v81
	v_min_f32_e32 v113, 0, v81
	v_mul_f32_e32 v81, 0x3db504f3, v82
	v_mul_f32_e64 v82, |v81|, s91
	v_max_f32_e32 v102, 0, v81
	v_min_f32_e32 v114, 0, v81
	v_mul_f32_e32 v81, 0x3db504f3, v83
	v_mul_f32_e64 v83, |v81|, s91
	v_exp_f32_e32 v83, v83
	v_max_f32_e32 v106, 0, v81
	v_min_f32_e32 v115, 0, v81
	v_mul_f32_e32 v81, 0x3db504f3, v84
	v_add_f32_e32 v83, 1.0, v83
	v_log_f32_e32 v104, v83
	v_mul_f32_e64 v83, |v81|, s91
	v_exp_f32_e32 v83, v83
	v_max_f32_e32 v84, 0, v81
	v_min_f32_e32 v81, 0, v81
	v_exp_f32_e32 v97, v97
	v_add_f32_e32 v83, 1.0, v83
	v_log_f32_e32 v83, v83
	v_mul_f32_e32 v90, 0x3db504f3, v90
	v_add_f32_e32 v97, 1.0, v97
	v_log_f32_e32 v98, v97
	v_fmac_f32_e32 v84, 0x3f317218, v83
	v_fmac_f32_e32 v81, 0xbf317218, v83
	v_mul_f32_e32 v83, 0x3db504f3, v85
	v_mul_f32_e64 v85, |v83|, s91
	v_exp_f32_e32 v85, v85
	v_max_f32_e32 v97, 0, v83
	v_min_f32_e32 v83, 0, v83
	v_max_f32_e32 v117, 0, v90
	v_add_f32_e32 v85, 1.0, v85
	v_log_f32_e32 v85, v85
	v_min_f32_e32 v101, 0, v90
	v_mul_f32_e32 v94, 0x3db504f3, v94
	v_min_f32_e32 v109, 0, v94
	v_fmac_f32_e32 v97, 0x3f317218, v85
	v_fmac_f32_e32 v83, 0xbf317218, v85
	v_mul_f32_e32 v85, 0x3db504f3, v86
	v_mul_f32_e64 v86, |v85|, s91
	v_exp_f32_e32 v86, v86
	v_cndmask_b32_e64 v108, 0, v97, s[70:71]
	v_cndmask_b32_e64 v84, 0, v84, s[72:73]
	v_cndmask_b32_e64 v83, v202, v83, s[70:71]
	v_add_f32_e32 v86, 1.0, v86
	v_log_f32_e32 v97, v86
	v_max_f32_e32 v86, 0, v85
	v_min_f32_e32 v85, 0, v85
	v_cndmask_b32_e64 v81, v202, v81, s[72:73]
	v_fmac_f32_e32 v85, 0xbf317218, v97
	v_fmac_f32_e32 v86, 0x3f317218, v97
	v_cndmask_b32_e64 v97, v202, v85, s[68:69]
	v_mul_f32_e32 v85, 0x3db504f3, v87
	v_mul_f32_e64 v87, |v85|, s91
	v_exp_f32_e32 v87, v87
	v_max_f32_e32 v99, 0, v85
	v_min_f32_e32 v85, 0, v85
	v_cndmask_b32_e64 v86, 0, v86, s[68:69]
	v_add_f32_e32 v87, 1.0, v87
	v_log_f32_e32 v87, v87
	v_mul_f32_e32 v64, 0x3db504f3, v64
	v_exp_f32_e32 v80, v80
	v_exp_f32_e32 v82, v82
	v_fmac_f32_e32 v99, 0x3f317218, v87
	v_fmac_f32_e32 v85, 0xbf317218, v87
	v_cndmask_b32_e64 v110, 0, v99, s[66:67]
	v_cndmask_b32_e64 v99, v202, v85, s[66:67]
	v_mul_f32_e32 v85, 0x3db504f3, v88
	v_mul_f32_e64 v87, |v85|, s91
	v_exp_f32_e32 v87, v87
	v_max_f32_e32 v116, 0, v85
	v_min_f32_e32 v85, 0, v85
	v_add_f32_e32 v80, 1.0, v80
	v_add_f32_e32 v87, 1.0, v87
	v_log_f32_e32 v88, v87
	v_mul_f32_e32 v87, 0x3db504f3, v89
	v_mul_f32_e64 v89, |v87|, s91
	v_exp_f32_e32 v89, v89
	v_max_f32_e32 v120, 0, v87
	v_min_f32_e32 v87, 0, v87
	v_log_f32_e32 v80, v80
	v_add_f32_e32 v89, 1.0, v89
	v_log_f32_e32 v118, v89
	v_mul_f32_e64 v89, |v90|, s91
	v_mul_f32_e32 v90, 0x3db504f3, v91
	v_mul_f32_e64 v91, |v90|, s91
	v_exp_f32_e32 v91, v91
	v_max_f32_e32 v121, 0, v90
	v_min_f32_e32 v103, 0, v90
	v_exp_f32_e32 v89, v89
	v_add_f32_e32 v91, 1.0, v91
	v_log_f32_e32 v119, v91
	v_mul_f32_e32 v91, 0x3db504f3, v92
	v_mul_f32_e64 v90, |v91|, s91
	v_max_f32_e32 v92, 0, v91
	v_min_f32_e32 v105, 0, v91
	v_mul_f32_e32 v91, 0x3db504f3, v93
	v_mul_f32_e64 v93, |v91|, s91
	v_exp_f32_e32 v93, v93
	v_max_f32_e32 v124, 0, v91
	v_min_f32_e32 v107, 0, v91
	v_mul_f32_e64 v91, |v94|, s91
	v_add_f32_e32 v93, 1.0, v93
	v_log_f32_e32 v122, v93
	v_max_f32_e32 v93, 0, v94
	v_mul_f32_e32 v94, 0x3db504f3, v95
	v_mul_f32_e64 v95, |v94|, s91
	v_add_f32_e32 v89, 1.0, v89
	v_exp_f32_e32 v95, v95
	v_log_f32_e32 v89, v89
	v_exp_f32_e32 v90, v90
	v_exp_f32_e32 v91, v91
	v_add_f32_e32 v95, 1.0, v95
	v_log_f32_e32 v123, v95
	v_max_f32_e32 v125, 0, v94
	v_min_f32_e32 v176, 0, v94
	v_pk_mul_f32 v[94:95], v[88:89], s[94:95] op_sel_hi:[1,0]
	v_pk_mul_f32 v[126:127], v[118:119], s[94:95] op_sel_hi:[1,0]
	v_sub_f32_e32 v85, v85, v94
	v_pk_fma_f32 v[88:89], v[88:89], s[94:95], v[116:117] op_sel_hi:[1,0,1]
	v_add_f32_e32 v90, 1.0, v90
	v_add_f32_e32 v91, 1.0, v91
	v_cndmask_b32_e64 v177, v202, v85, s[64:65]
	v_sub_f32_e32 v85, v87, v126
	v_cndmask_b32_e64 v117, 0, v89, s[62:63]
	v_cndmask_b32_e64 v116, 0, v88, s[64:65]
	v_pk_fma_f32 v[88:89], v[118:119], s[94:95], v[120:121] op_sel_hi:[1,0,1]
	v_log_f32_e32 v90, v90
	v_log_f32_e32 v91, v91
	v_cndmask_b32_e64 v178, v202, v85, s[60:61]
	v_sub_f32_e32 v85, v101, v95
	v_cndmask_b32_e64 v95, 0, v89, s[58:59]
	v_cndmask_b32_e64 v94, 0, v88, s[60:61]
	v_pk_add_f32 v[88:89], v[116:117], v[94:95]
	v_cndmask_b32_e64 v101, v202, v85, s[62:63]
	v_sub_f32_e32 v85, v103, v127
	v_pk_add_f32 v[88:89], v[88:89], v[88:89] op_sel:[0,1] op_sel_hi:[1,0]
	v_cndmask_b32_e64 v103, v202, v85, s[58:59]
	v_mov_b32_e32 v85, v88
	v_mov_b32_e32 v87, v88
	s_nop 1
	v_permlane32_swap_b32_e32 v85, v87
	v_pk_mul_f32 v[118:119], v[90:91], s[94:95] op_sel_hi:[1,0]
	v_cndmask_b32_e64 v111, v85, v87, s[4:5]
	v_sub_f32_e32 v85, v105, v118
	v_pk_mul_f32 v[120:121], v[122:123], s[94:95] op_sel_hi:[1,0]
	v_pk_fma_f32 v[90:91], v[90:91], s[94:95], v[92:93] op_sel_hi:[1,0,1]
	v_cndmask_b32_e64 v105, v202, v85, s[56:57]
	v_sub_f32_e32 v85, v107, v120
	v_cndmask_b32_e64 v127, 0, v91, s[54:55]
	v_cndmask_b32_e64 v126, 0, v90, s[56:57]
	v_pk_fma_f32 v[90:91], v[122:123], s[94:95], v[124:125] op_sel_hi:[1,0,1]
	v_cndmask_b32_e64 v107, v202, v85, s[52:53]
	v_sub_f32_e32 v85, v109, v119
	v_cndmask_b32_e64 v119, 0, v91, s[50:51]
	v_cndmask_b32_e64 v118, 0, v90, s[52:53]
	v_pk_add_f32 v[90:91], v[126:127], v[118:119]
	v_cndmask_b32_e64 v92, v202, v85, s[54:55]
	v_sub_f32_e32 v85, v176, v121
	v_pk_add_f32 v[90:91], v[90:91], v[90:91] op_sel:[0,1] op_sel_hi:[1,0]
	v_cndmask_b32_e64 v120, v202, v85, s[50:51]
	v_mov_b32_e32 v85, v90
	v_mov_b32_e32 v87, v90
	s_nop 1
	v_permlane32_swap_b32_e32 v85, v87
	v_cndmask_b32_e64 v109, v85, v87, s[4:5]
	v_mov_b32_e32 v85, v90
	v_mov_b32_e32 v87, v88
	v_pk_add_f32 v[90:91], v[84:85], v[108:109]
	v_pk_add_f32 v[84:85], v[86:87], v[110:111]
	v_add_f32_e32 v82, 1.0, v82
	v_pk_add_f32 v[84:85], v[90:91], v[84:85]
	v_log_f32_e32 v82, v82
	v_mov_b32_e32 v87, v84
	v_mov_b32_e32 v88, v84
	s_nop 1
	v_permlane32_swap_b32_e32 v87, v88
	v_cndmask_b32_e64 v87, v87, v88, s[4:5]
	v_add_f32_e32 v116, v84, v87
	v_add_f32_e32 v84, v195, v85
	v_cndmask_b32_e64 v87, 0, v87, s[4:5]
	v_add_f32_e32 v87, v87, v84
	v_add_f32_e32 v88, v110, v87
	v_add_f32_e32 v86, v86, v88
	v_sub_f32_e32 v83, v83, v86
	v_mul_f32_e32 v83, 0x3fb8aa3b, v83
	v_sub_f32_e32 v84, v99, v87
	v_sub_f32_e32 v87, v97, v88
	v_exp_f32_e32 v88, v83
	v_add_f32_e32 v83, v108, v86
	v_sub_f32_e32 v81, v81, v83
	v_mul_f32_e32 v81, 0x3fb8aa3b, v81
	v_exp_f32_e32 v90, v81
	v_add_f32_e32 v81, v195, v91
	v_cndmask_b32_e64 v83, 0, v111, s[4:5]
	v_add_f32_e32 v81, v83, v81
	v_sub_f32_e32 v83, v103, v81
	v_mul_f32_e32 v83, 0x3fb8aa3b, v83
	v_add_f32_e32 v81, v95, v81
	v_exp_f32_e32 v86, v83
	v_sub_f32_e32 v83, v101, v81
	v_mul_f32_e32 v83, 0x3fb8aa3b, v83
	v_add_f32_e32 v81, v117, v81
	v_exp_f32_e32 v89, v83
	v_sub_f32_e32 v83, v178, v81
	v_add_f32_e32 v81, v94, v81
	v_sub_f32_e32 v81, v177, v81
	v_mul_f32_e32 v81, 0x3fb8aa3b, v81
	v_exp_f32_e32 v93, v81
	v_cndmask_b32_e64 v81, 0, v109, s[4:5]
	v_mul_f32_e32 v83, 0x3fb8aa3b, v83
	v_add_f32_e32 v81, v218, v81
	v_exp_f32_e32 v91, v83
	v_sub_f32_e32 v83, v120, v81
	v_mul_f32_e32 v83, 0x3fb8aa3b, v83
	v_add_f32_e32 v81, v81, v119
	v_exp_f32_e32 v94, v83
	v_sub_f32_e32 v83, v92, v81
	v_mul_f32_e32 v83, 0x3fb8aa3b, v83
	v_add_f32_e32 v81, v127, v81
	v_exp_f32_e32 v95, v83
	v_sub_f32_e32 v83, v107, v81
	v_add_f32_e32 v81, v118, v81
	v_sub_f32_e32 v81, v105, v81
	v_mul_f32_e32 v81, 0x3fb8aa3b, v81
	v_exp_f32_e32 v109, v81
	v_mul_f32_e64 v81, |v64|, s91
	v_max_f32_e32 v97, 0, v64
	v_min_f32_e32 v92, 0, v64
	v_mul_f32_e32 v64, 0x3db504f3, v65
	v_mul_f32_e64 v65, |v64|, s91
	v_exp_f32_e32 v65, v65
	v_max_f32_e32 v101, 0, v64
	v_min_f32_e32 v110, 0, v64
	v_mul_f32_e32 v64, 0x3db504f3, v66
	v_add_f32_e32 v65, 1.0, v65
	v_log_f32_e32 v99, v65
	v_mul_f32_e64 v65, |v64|, s91
	v_exp_f32_e32 v65, v65
	v_mul_f32_e32 v83, 0x3fb8aa3b, v83
	v_max_f32_e32 v103, 0, v64
	v_min_f32_e32 v111, 0, v64
	v_add_f32_e32 v65, 1.0, v65
	v_mul_f32_e32 v64, 0x3db504f3, v67
	v_exp_f32_e32 v108, v83
	v_log_f32_e32 v83, v65
	v_mul_f32_e64 v65, |v64|, s91
	v_exp_f32_e32 v65, v65
	v_max_f32_e32 v107, 0, v64
	v_min_f32_e32 v117, 0, v64
	v_mul_f32_e32 v64, 0x3db504f3, v68
	v_add_f32_e32 v65, 1.0, v65
	v_log_f32_e32 v105, v65
	v_mul_f32_e64 v65, |v64|, s91
	v_exp_f32_e32 v65, v65
	v_max_f32_e32 v66, 0, v64
	v_min_f32_e32 v64, 0, v64
	v_exp_f32_e32 v81, v81
	v_add_f32_e32 v65, 1.0, v65
	v_log_f32_e32 v65, v65
	v_pk_mul_f32 v[222:223], v[104:105], s[94:95] op_sel_hi:[1,0]
	v_add_f32_e32 v81, 1.0, v81
	v_log_f32_e32 v81, v81
	v_fmac_f32_e32 v66, 0x3f317218, v65
	v_fmac_f32_e32 v64, 0xbf317218, v65
	v_mul_f32_e32 v65, 0x3db504f3, v69
	v_cndmask_b32_e64 v118, v202, v64, s[48:49]
	v_mul_f32_e64 v64, |v65|, s91
	v_exp_f32_e32 v64, v64
	v_mul_f32_e32 v84, 0x3fb8aa3b, v84
	v_exp_f32_e32 v84, v84
	v_mul_f32_e32 v87, 0x3fb8aa3b, v87
	v_add_f32_e32 v64, 1.0, v64
	v_log_f32_e32 v67, v64
	v_max_f32_e32 v64, 0, v65
	v_min_f32_e32 v65, 0, v65
	v_cndmask_b32_e64 v66, 0, v66, s[48:49]
	v_fmac_f32_e32 v65, 0xbf317218, v67
	v_cndmask_b32_e64 v119, v202, v65, s[46:47]
	v_mul_f32_e32 v65, 0x3db504f3, v70
	v_fmac_f32_e32 v64, 0x3f317218, v67
	v_mul_f32_e64 v67, |v65|, s91
	v_exp_f32_e32 v67, v67
	v_max_f32_e32 v68, 0, v65
	v_min_f32_e32 v65, 0, v65
	v_cndmask_b32_e64 v64, 0, v64, s[46:47]
	v_add_f32_e32 v67, 1.0, v67
	v_log_f32_e32 v67, v67
	v_exp_f32_e32 v87, v87
	v_fmac_f32_e32 v65, 0xbf317218, v67
	v_cndmask_b32_e64 v120, v202, v65, s[44:45]
	v_mul_f32_e32 v65, 0x3db504f3, v71
	v_fmac_f32_e32 v68, 0x3f317218, v67
	v_mul_f32_e64 v67, |v65|, s91
	v_exp_f32_e32 v67, v67
	v_max_f32_e32 v69, 0, v65
	v_min_f32_e32 v65, 0, v65
	v_cndmask_b32_e64 v68, 0, v68, s[44:45]
	v_add_f32_e32 v67, 1.0, v67
	v_log_f32_e32 v67, v67
	s_nop 0
	v_fmac_f32_e32 v65, 0xbf317218, v67
	v_cndmask_b32_e64 v121, v202, v65, s[42:43]
	v_mul_f32_e32 v65, 0x3db504f3, v72
	v_fmac_f32_e32 v69, 0x3f317218, v67
	v_mul_f32_e64 v67, |v65|, s91
	v_exp_f32_e32 v67, v67
	v_cndmask_b32_e64 v70, 0, v69, s[42:43]
	v_max_f32_e32 v122, 0, v65
	v_min_f32_e32 v65, 0, v65
	v_add_f32_e32 v67, 1.0, v67
	v_log_f32_e32 v72, v67
	v_mul_f32_e32 v67, 0x3db504f3, v73
	v_mul_f32_e64 v69, |v67|, s91
	v_exp_f32_e32 v69, v69
	v_max_f32_e32 v126, 0, v67
	v_min_f32_e32 v67, 0, v67
	v_add_f32_e32 v69, 1.0, v69
	v_log_f32_e32 v124, v69
	v_mul_f32_e32 v69, 0x3db504f3, v74
	v_mul_f32_e64 v71, |v69|, s91
	v_exp_f32_e32 v71, v71
	v_max_f32_e32 v123, 0, v69
	v_min_f32_e32 v69, 0, v69
	v_add_f32_e32 v71, 1.0, v71
	v_log_f32_e32 v73, v71
	v_mul_f32_e32 v71, 0x3db504f3, v75
	v_mul_f32_e64 v74, |v71|, s91
	v_exp_f32_e32 v74, v74
	v_max_f32_e32 v127, 0, v71
	v_min_f32_e32 v71, 0, v71
	v_add_f32_e32 v74, 1.0, v74
	v_log_f32_e32 v125, v74
	v_mul_f32_e32 v74, 0x3db504f3, v76
	v_mul_f32_e64 v75, |v74|, s91
	v_exp_f32_e32 v75, v75
	v_max_f32_e32 v176, 0, v74
	v_min_f32_e32 v182, 0, v74
	v_mul_f32_e32 v74, 0x3db504f3, v77
	v_add_f32_e32 v75, 1.0, v75
	v_log_f32_e32 v76, v75
	v_mul_f32_e64 v75, |v74|, s91
	v_exp_f32_e32 v75, v75
	v_max_f32_e32 v180, 0, v74
	v_min_f32_e32 v183, 0, v74
	v_mul_f32_e32 v74, 0x3db504f3, v78
	v_add_f32_e32 v75, 1.0, v75
	v_log_f32_e32 v178, v75
	v_mul_f32_e64 v75, |v74|, s91
	v_exp_f32_e32 v75, v75
	v_max_f32_e32 v177, 0, v74
	v_min_f32_e32 v219, 0, v74
	v_mul_f32_e32 v74, 0x3db504f3, v79
	v_add_f32_e32 v75, 1.0, v75
	v_log_f32_e32 v77, v75
	v_mul_f32_e64 v75, |v74|, s91
	v_exp_f32_e32 v75, v75
	v_max_f32_e32 v181, 0, v74
	v_min_f32_e32 v220, 0, v74
	v_pk_mul_f32 v[78:79], v[124:125], s[94:95] op_sel_hi:[1,0]
	v_add_f32_e32 v75, 1.0, v75
	v_log_f32_e32 v179, v75
	v_pk_mul_f32 v[74:75], v[72:73], s[94:95] op_sel_hi:[1,0]
	v_pk_fma_f32 v[72:73], v[72:73], s[94:95], v[122:123] op_sel_hi:[1,0,1]
	v_sub_f32_e32 v65, v65, v74
	v_cndmask_b32_e64 v224, v202, v65, s[40:41]
	v_sub_f32_e32 v65, v67, v78
	v_cndmask_b32_e64 v225, v202, v65, s[36:37]
	v_sub_f32_e32 v65, v69, v75
	v_cndmask_b32_e64 v226, v202, v65, s[38:39]
	v_pk_fma_f32 v[74:75], v[124:125], s[94:95], v[126:127] op_sel_hi:[1,0,1]
	v_sub_f32_e32 v65, v71, v79
	v_pk_mul_f32 v[122:123], v[76:77], s[94:95] op_sel_hi:[1,0]
	v_cndmask_b32_e64 v73, 0, v73, s[38:39]
	v_cndmask_b32_e64 v72, 0, v72, s[40:41]
	v_cndmask_b32_e64 v75, 0, v75, s[34:35]
	v_cndmask_b32_e64 v74, 0, v74, s[36:37]
	v_cndmask_b32_e64 v227, v202, v65, s[34:35]
	v_sub_f32_e32 v65, v182, v122
	v_pk_mul_f32 v[124:125], v[178:179], s[94:95] op_sel_hi:[1,0]
	v_pk_add_f32 v[78:79], v[72:73], v[74:75]
	v_cndmask_b32_e64 v72, v202, v65, s[30:31]
	v_sub_f32_e32 v65, v183, v124
	v_cndmask_b32_e64 v228, v202, v65, s[26:27]
	v_sub_f32_e32 v65, v219, v123
	v_cndmask_b32_e64 v219, v202, v65, s[28:29]
	v_sub_f32_e32 v65, v220, v125
	v_pk_mul_f32 v[126:127], v[80:81], s[94:95] op_sel_hi:[1,0]
	v_pk_mul_f32 v[220:221], v[98:99], s[94:95] op_sel_hi:[1,0]
	v_cndmask_b32_e64 v229, v202, v65, s[24:25]
	v_sub_f32_e32 v65, v112, v126
	v_sub_f32_e32 v67, v113, v220
	v_pk_mul_f32 v[112:113], v[82:83], s[94:95] op_sel_hi:[1,0]
	v_pk_fma_f32 v[80:81], v[80:81], s[94:95], v[96:97] op_sel_hi:[1,0,1]
	v_pk_fma_f32 v[96:97], v[98:99], s[94:95], v[100:101] op_sel_hi:[1,0,1]
	v_pk_fma_f32 v[82:83], v[82:83], s[94:95], v[102:103] op_sel_hi:[1,0,1]
	v_pk_fma_f32 v[98:99], v[104:105], s[94:95], v[106:107] op_sel_hi:[1,0,1]
	v_cndmask_b32_e32 v81, 0, v81, vcc
	v_cndmask_b32_e64 v80, 0, v80, s[22:23]
	v_cndmask_b32_e64 v97, 0, v97, s[10:11]
	v_cndmask_b32_e64 v96, 0, v96, s[20:21]
	v_cndmask_b32_e64 v83, 0, v83, s[12:13]
	v_cndmask_b32_e64 v82, 0, v82, s[18:19]
	v_cndmask_b32_e64 v99, 0, v99, s[14:15]
	v_cndmask_b32_e64 v98, 0, v98, s[16:17]
	v_pk_fma_f32 v[76:77], v[76:77], s[94:95], v[176:177] op_sel_hi:[1,0,1]
	v_pk_fma_f32 v[122:123], v[178:179], s[94:95], v[180:181] op_sel_hi:[1,0,1]
	v_pk_add_f32 v[80:81], v[80:81], v[96:97]
	v_pk_add_f32 v[100:101], v[82:83], v[98:99]
	v_pk_add_f32 v[78:79], v[78:79], v[78:79] op_sel:[0,1] op_sel_hi:[1,0]
	v_cndmask_b32_e64 v77, 0, v77, s[28:29]
	v_cndmask_b32_e64 v76, 0, v76, s[30:31]
	v_cndmask_b32_e64 v123, 0, v123, s[24:25]
	v_cndmask_b32_e64 v122, 0, v122, s[26:27]
	v_pk_add_f32 v[80:81], v[80:81], v[100:101]
	v_pk_add_f32 v[124:125], v[76:77], v[122:123]
	v_mov_b32_e32 v76, v80
	v_mov_b32_e32 v79, v80
	s_nop 1
	v_permlane32_swap_b32_e32 v76, v79
	v_cndmask_b32_e64 v100, v76, v79, s[4:5]
	v_add_f32_e32 v102, v116, v85
	v_sub_f32_e32 v71, v115, v222
	v_add_f32_e32 v76, v195, v102
	v_cndmask_b32_e64 v79, 0, v100, s[4:5]
	v_sub_f32_e32 v69, v114, v112
	v_cndmask_b32_e64 v71, v202, v71, s[16:17]
	v_add_f32_e32 v76, v79, v76
	v_cndmask_b32_e64 v69, v202, v69, s[18:19]
	v_sub_f32_e32 v71, v71, v76
	v_add_f32_e32 v76, v98, v76
	v_cndmask_b32_e64 v67, v202, v67, s[20:21]
	v_sub_f32_e32 v69, v69, v76
	v_add_f32_e32 v76, v82, v76
	v_cndmask_b32_e64 v65, v202, v65, s[22:23]
	v_sub_f32_e32 v67, v67, v76
	v_add_f32_e32 v76, v96, v76
	v_sub_f32_e32 v65, v65, v76
	v_mul_f32_e32 v67, 0x3fb8aa3b, v67
	v_mul_f32_e32 v65, 0x3fb8aa3b, v65
	v_exp_f32_e32 v67, v67
	v_exp_f32_e32 v65, v65
	s_nop 0
	v_cvt_pk_bf16_f32 v176, v65, v67
	v_mov_b32_e32 v65, v81
	v_mov_b32_e32 v67, v81
	s_nop 1
	v_permlane32_swap_b32_e32 v65, v67
	v_mul_f32_e32 v69, 0x3fb8aa3b, v69
	v_cndmask_b32_e64 v101, v65, v67, s[4:5]
	v_mov_b32_e32 v65, v78
	v_mov_b32_e32 v67, v78
	v_pk_add_f32 v[124:125], v[124:125], v[124:125] op_sel:[0,1] op_sel_hi:[1,0]
	v_mul_f32_e32 v71, 0x3fb8aa3b, v71
	v_exp_f32_e32 v69, v69
	v_permlane32_swap_b32_e32 v65, v67
	v_exp_f32_e32 v71, v71
	s_nop 0
	v_cvt_pk_bf16_f32 v177, v69, v71
	v_cndmask_b32_e64 v65, v65, v67, s[4:5]
	v_mov_b32_e32 v67, v124
	v_mov_b32_e32 v69, v124
	s_nop 1
	v_permlane32_swap_b32_e32 v67, v69
	v_cndmask_b32_e64 v71, v67, v69, s[4:5]
	v_mov_b32_e32 v69, v124
	v_mov_b32_e32 v67, v78
	v_cvt_pk_bf16_f32 v178, v90, v88
	v_cvt_pk_bf16_f32 v179, v87, v84
	v_pk_add_f32 v[84:85], v[68:69], v[70:71]
	v_pk_add_f32 v[66:67], v[66:67], v[64:65]
	v_pk_add_f32 v[78:79], v[80:81], v[100:101]
	v_pk_add_f32 v[66:67], v[66:67], v[84:85]
	v_cndmask_b32_e64 v65, 0, v65, s[4:5]
	v_mov_b32_e32 v69, v66
	v_mov_b32_e32 v76, v66
	s_nop 1
	v_permlane32_swap_b32_e32 v69, v76
	v_cndmask_b32_e64 v69, v69, v76, s[4:5]
	v_add_f32_e32 v66, v66, v69
	v_add_f32_e32 v103, v66, v67
	v_pk_add_f32 v[78:79], v[78:79], v[102:103]
	v_cndmask_b32_e64 v69, 0, v69, s[4:5]
	v_add_f32_e32 v66, v195, v78
	v_add_f32_e32 v67, v66, v67
	v_add_f32_e32 v67, v69, v67
	v_sub_f32_e32 v69, v121, v67
	v_add_f32_e32 v67, v70, v67
	v_sub_f32_e32 v70, v120, v67
	v_add_f32_e32 v67, v68, v67
	v_sub_f32_e32 v68, v119, v67
	v_add_f32_e32 v64, v64, v67
	v_add_f32_e32 v67, v66, v85
	v_cvt_pk_bf16_f32 v180, v93, v91
	v_cvt_pk_bf16_f32 v181, v89, v86
	v_sub_f32_e32 v82, v117, v223
	v_add_f32_e32 v84, v66, v103
	v_cndmask_b32_e64 v86, 0, v101, s[4:5]
	v_add_f32_e32 v65, v65, v67
	v_add_f32_e32 v66, 0, v66
	v_cndmask_b32_e64 v71, 0, v71, s[4:5]
	v_cndmask_b32_e64 v82, v202, v82, s[14:15]
	v_add_f32_e32 v84, v86, v84
	v_sub_f32_e32 v67, v227, v65
	v_add_f32_e32 v65, v75, v65
	v_add_f32_e32 v66, v66, v71
	v_sub_f32_e32 v80, v110, v221
	v_sub_f32_e32 v82, v82, v84
	v_add_f32_e32 v84, v99, v84
	v_sub_f32_e32 v75, v226, v65
	v_add_f32_e32 v65, v73, v65
	v_sub_f32_e32 v71, v229, v66
	v_add_f32_e32 v66, v123, v66
	v_sub_f32_e32 v76, v92, v127
	v_cndmask_b32_e64 v80, v202, v80, s[10:11]
	v_sub_f32_e32 v81, v111, v113
	v_add_f32_e32 v83, v83, v84
	v_sub_f32_e32 v73, v225, v65
	v_add_f32_e32 v65, v74, v65
	v_sub_f32_e32 v74, v219, v66
	v_add_f32_e32 v66, v77, v66
	v_cndmask_b32_e32 v76, v202, v76, vcc
	v_cndmask_b32_e64 v81, v202, v81, s[12:13]
	v_sub_f32_e32 v80, v80, v83
	v_add_f32_e32 v83, v97, v83
	v_sub_f32_e32 v77, v228, v66
	v_add_f32_e32 v66, v122, v66
	v_sub_f32_e32 v81, v81, v84
	v_sub_f32_e32 v76, v76, v83
	v_sub_f32_e32 v64, v118, v64
	v_sub_f32_e32 v65, v224, v65
	v_sub_f32_e32 v66, v72, v66
	v_mul_f32_e32 v82, 0x3fb8aa3b, v82
	v_mul_f32_e32 v81, 0x3fb8aa3b, v81
	v_mul_f32_e32 v80, 0x3fb8aa3b, v80
	v_mul_f32_e32 v76, 0x3fb8aa3b, v76
	v_mul_f32_e32 v69, 0x3fb8aa3b, v69
	v_mul_f32_e32 v70, 0x3fb8aa3b, v70
	v_mul_f32_e32 v68, 0x3fb8aa3b, v68
	v_mul_f32_e32 v64, 0x3fb8aa3b, v64
	v_mul_f32_e32 v67, 0x3fb8aa3b, v67
	v_mul_f32_e32 v75, 0x3fb8aa3b, v75
	v_mul_f32_e32 v73, 0x3fb8aa3b, v73
	v_mul_f32_e32 v65, 0x3fb8aa3b, v65
	v_mul_f32_e32 v71, 0x3fb8aa3b, v71
	v_mul_f32_e32 v74, 0x3fb8aa3b, v74
	v_mul_f32_e32 v77, 0x3fb8aa3b, v77
	v_mul_f32_e32 v66, 0x3fb8aa3b, v66
	v_exp_f32_e32 v82, v82
	v_exp_f32_e32 v81, v81
	v_exp_f32_e32 v80, v80
	v_exp_f32_e32 v76, v76
	v_exp_f32_e32 v69, v69
	v_exp_f32_e32 v70, v70
	v_exp_f32_e32 v68, v68
	v_exp_f32_e32 v64, v64
	v_exp_f32_e32 v67, v67
	v_exp_f32_e32 v75, v75
	v_exp_f32_e32 v73, v73
	v_exp_f32_e32 v65, v65
	v_exp_f32_e32 v71, v71
	v_exp_f32_e32 v74, v74
	v_exp_f32_e32 v77, v77
	v_exp_f32_e32 v66, v66
	v_cvt_pk_bf16_f32 v182, v109, v108
	v_cvt_pk_bf16_f32 v183, v95, v94
	v_cvt_pk_bf16_f32 v220, v76, v80
	v_cvt_pk_bf16_f32 v221, v81, v82
	v_cvt_pk_bf16_f32 v222, v64, v68
	v_cvt_pk_bf16_f32 v223, v70, v69
	v_cvt_pk_bf16_f32 v224, v65, v73
	v_cvt_pk_bf16_f32 v225, v75, v67
	v_cvt_pk_bf16_f32 v226, v66, v77
	v_cvt_pk_bf16_f32 v227, v74, v71
	v_add_f32_e32 v219, v78, v79
	v_permlane32_swap_b32_e32 v176, v178
	v_permlane32_swap_b32_e32 v177, v179
	v_permlane32_swap_b32_e32 v180, v182
	v_permlane32_swap_b32_e32 v181, v183
	v_permlane32_swap_b32_e32 v220, v222
	v_permlane32_swap_b32_e32 v221, v223
	v_permlane32_swap_b32_e32 v224, v226
	v_permlane32_swap_b32_e32 v225, v227
	ds_read_b64_tr_b16 v[80:81], v207 offset:0x4000
	ds_read_b64_tr_b16 v[82:83], v207 offset:0x4800
	ds_read_b64_tr_b16 v[84:85], v207 offset:0x5000
	ds_read_b64_tr_b16 v[86:87], v207 offset:0x5800
	ds_read_b64_tr_b16 v[88:89], v207 offset:0x6000
	ds_read_b64_tr_b16 v[90:91], v207 offset:0x6800
	ds_read_b64_tr_b16 v[92:93], v207 offset:0x7000
	ds_read_b64_tr_b16 v[94:95], v207 offset:0x7800
	s_waitcnt lgkmcnt(0)
	s_nop 0
	v_mfma_f32_32x32x16_bf16 v[64:79], v[220:223], v[80:83], v[48:63]
	ds_read_b64_tr_b16 v[96:97], v207 offset:0x4200
	ds_read_b64_tr_b16 v[98:99], v207 offset:0x4a00
	ds_read_b64_tr_b16 v[100:101], v207 offset:0x5200
	ds_read_b64_tr_b16 v[102:103], v207 offset:0x5a00
	ds_read_b64_tr_b16 v[104:105], v207 offset:0x6200
	ds_read_b64_tr_b16 v[106:107], v207 offset:0x6a00
	ds_read_b64_tr_b16 v[108:109], v207 offset:0x7200
	v_mfma_f32_32x32x16_bf16 v[64:79], v[224:227], v[84:87], v[64:79]
	ds_read_b64_tr_b16 v[110:111], v207 offset:0x7a00
	s_waitcnt lgkmcnt(0)
	v_mfma_f32_32x32x16_bf16 v[64:79], v[176:179], v[88:91], v[64:79]
	v_mfma_f32_32x32x16_bf16 v[64:79], v[180:183], v[92:95], v[64:79]
	v_mfma_f32_32x32x16_bf16 v[80:95], v[220:223], v[96:99], v[32:47]
	ds_read_b64_tr_b16 v[112:113], v207 offset:0x4400
	ds_read_b64_tr_b16 v[114:115], v207 offset:0x4c00
	ds_read_b64_tr_b16 v[116:117], v207 offset:0x5400
	ds_read_b64_tr_b16 v[118:119], v207 offset:0x5c00
	ds_read_b64_tr_b16 v[120:121], v207 offset:0x6400
	ds_read_b64_tr_b16 v[122:123], v207 offset:0x6c00
	ds_read_b64_tr_b16 v[124:125], v207 offset:0x7400
	v_mfma_f32_32x32x16_bf16 v[80:95], v[224:227], v[100:103], v[80:95]
	ds_read_b64_tr_b16 v[126:127], v207 offset:0x7c00
	s_waitcnt lgkmcnt(0)
	v_mfma_f32_32x32x16_bf16 v[80:95], v[176:179], v[104:107], v[80:95]
	v_mfma_f32_32x32x16_bf16 v[80:95], v[180:183], v[108:111], v[80:95]
	v_mfma_f32_32x32x16_bf16 v[96:111], v[220:223], v[112:115], v[16:31]
	ds_read_b64_tr_b16 v[228:229], v207 offset:0x4600
	ds_read_b64_tr_b16 v[230:231], v207 offset:0x4e00
	ds_read_b64_tr_b16 v[232:233], v207 offset:0x5600
	ds_read_b64_tr_b16 v[234:235], v207 offset:0x5e00
	ds_read_b64_tr_b16 v[236:237], v207 offset:0x6600
	ds_read_b64_tr_b16 v[238:239], v207 offset:0x6e00
	ds_read_b64_tr_b16 v[240:241], v207 offset:0x7600
	v_mfma_f32_32x32x16_bf16 v[96:111], v[224:227], v[116:119], v[96:111]
	ds_read_b64_tr_b16 v[242:243], v207 offset:0x7e00
	s_waitcnt lgkmcnt(0)
	v_mfma_f32_32x32x16_bf16 v[96:111], v[176:179], v[120:123], v[96:111]
	v_mfma_f32_32x32x16_bf16 v[96:111], v[180:183], v[124:127], v[96:111]
	v_mfma_f32_32x32x16_bf16 v[112:127], v[220:223], v[228:231], v[0:15]
	s_mov_b64 s[0:1], 0
	v_mfma_f32_32x32x16_bf16 v[112:127], v[224:227], v[232:235], v[112:127]
	v_mfma_f32_32x32x16_bf16 v[112:127], v[176:179], v[236:239], v[112:127]
	v_mfma_f32_32x32x16_bf16 v[112:127], v[180:183], v[240:243], v[112:127]
.LBB0_496:
	s_andn2_b64 vcc, exec, s[0:1]
	s_cbranch_vccnz .LBB0_498
	ds_read_b128 v[64:67], v213 offset:32768
	s_nop 3
	ds_read_b128 v[96:99], v213 offset:32896
	ds_read_b128 v[80:83], v213 offset:40960
	ds_read_b128 v[100:103], v213 offset:41088
	ds_read_b128 v[104:107], v214 offset:40960
	ds_read_b128 v[108:111], v214 offset:41088
	v_cmp_lt_i32_e32 vcc, 40, v217
	s_waitcnt lgkmcnt(3)
	v_mfma_f32_32x32x16_bf16 v[80:95], v[80:83], v[128:131], 0
	v_cmp_lt_i32_e64 s[10:11], 50, v217
	v_cmp_lt_i32_e64 s[0:1], 49, v217
	v_cmp_lt_i32_e64 s[12:13], 34, v217
	v_cmp_lt_i32_e64 s[14:15], 35, v217
	s_waitcnt lgkmcnt(1)
	v_mfma_f32_32x32x16_bf16 v[80:95], v[104:107], v[132:135], v[80:95]
	ds_read_b128 v[104:107], v215 offset:40960
	ds_read_b128 v[112:115], v215 offset:41088
	s_waitcnt lgkmcnt(1)
	v_mfma_f32_32x32x16_bf16 v[80:95], v[104:107], v[136:139], v[80:95]
	ds_read_b128 v[104:107], v216 offset:40960
	ds_read_b128 v[120:123], v216 offset:41088
	s_waitcnt lgkmcnt(1)
	v_mfma_f32_32x32x16_bf16 v[80:95], v[104:107], v[140:143], v[80:95]
	v_mfma_f32_32x32x16_bf16 v[80:95], v[100:103], v[144:147], v[80:95]
	v_mfma_f32_32x32x16_bf16 v[64:79], v[64:67], v[128:131], 0
	v_mfma_f32_32x32x16_bf16 v[80:95], v[108:111], v[148:151], v[80:95]
	v_mfma_f32_32x32x16_bf16 v[80:95], v[112:115], v[152:155], v[80:95]
	ds_read_b128 v[124:127], v214 offset:32768
	ds_read_b128 v[108:111], v214 offset:32896
	ds_read_b128 v[116:119], v215 offset:32768
	ds_read_b128 v[104:107], v215 offset:32896
	ds_read_b128 v[112:115], v216 offset:32768
	ds_read_b128 v[100:103], v216 offset:32896
	s_waitcnt lgkmcnt(5)
	v_mfma_f32_32x32x16_bf16 v[64:79], v[124:127], v[132:135], v[64:79]
	s_waitcnt lgkmcnt(3)
	v_mfma_f32_32x32x16_bf16 v[64:79], v[116:119], v[136:139], v[64:79]
	v_mfma_f32_32x32x16_bf16 v[80:95], v[120:123], v[156:159], v[80:95]
	s_waitcnt lgkmcnt(1)
	v_mfma_f32_32x32x16_bf16 v[64:79], v[112:115], v[140:143], v[64:79]
	s_nop 9
	v_mul_f32_e32 v80, 0x3db504f3, v80
	v_mul_f32_e32 v81, 0x3db504f3, v81
	v_mul_f32_e32 v120, 0x3db504f3, v82
	v_mul_f32_e32 v83, 0x3db504f3, v83
	v_mul_f32_e32 v121, 0x3db504f3, v84
	v_mul_f32_e32 v85, 0x3db504f3, v85
	v_mul_f32_e32 v123, 0x3db504f3, v86
	v_mul_f32_e64 v122, |v80|, s91
	v_max_f32_e32 v86, 0, v80
	v_min_f32_e32 v181, 0, v80
	v_mul_f32_e64 v176, |v81|, s91
	v_max_f32_e32 v84, 0, v81
	v_min_f32_e32 v180, 0, v81
	v_mul_f32_e64 v81, |v120|, s91
	v_max_f32_e32 v82, 0, v120
	v_min_f32_e32 v179, 0, v120
	v_mul_f32_e64 v120, |v83|, s91
	v_max_f32_e32 v80, 0, v83
	v_min_f32_e32 v178, 0, v83
	v_mul_f32_e64 v83, |v121|, s91
	v_mul_f32_e64 v182, |v85|, s91
	v_exp_f32_e32 v122, v122
	v_exp_f32_e32 v81, v81
	v_exp_f32_e32 v83, v83
	v_exp_f32_e32 v182, v182
	v_mfma_f32_32x32x16_bf16 v[64:79], v[96:99], v[144:147], v[64:79]
	v_add_f32_e32 v122, 1.0, v122
	v_add_f32_e32 v81, 1.0, v81
	v_add_f32_e32 v83, 1.0, v83
	v_add_f32_e32 v125, 1.0, v182
	v_log_f32_e32 v126, v122
	v_log_f32_e32 v122, v81
	v_log_f32_e32 v81, v83
	v_exp_f32_e32 v176, v176
	v_log_f32_e32 v83, v125
	v_max_f32_e32 v177, 0, v121
	v_min_f32_e32 v121, 0, v121
	v_max_f32_e32 v183, 0, v85
	v_min_f32_e32 v85, 0, v85
	v_fmac_f32_e32 v177, 0x3f317218, v81
	v_fmac_f32_e32 v121, 0xbf317218, v81
	v_mul_f32_e32 v87, 0x3db504f3, v87
	v_mul_f32_e64 v219, |v123|, s91
	v_add_f32_e32 v124, 1.0, v176
	v_fmac_f32_e32 v85, 0xbf317218, v83
	v_cndmask_b32_e32 v176, 0, v177, vcc
	v_cndmask_b32_e32 v81, v202, v121, vcc
	v_cmp_lt_i32_e32 vcc, 41, v217
	v_mfma_f32_32x32x16_bf16 v[64:79], v[108:111], v[148:151], v[64:79]
	v_exp_f32_e32 v219, v219
	v_fmac_f32_e32 v183, 0x3f317218, v83
	v_cndmask_b32_e32 v83, v202, v85, vcc
	v_mul_f32_e64 v85, |v87|, s91
	v_exp_f32_e32 v85, v85
	v_add_f32_e32 v127, 1.0, v219
	v_log_f32_e32 v125, v127
	v_mul_f32_e32 v113, 0x3db504f3, v88
	v_add_f32_e32 v85, 1.0, v85
	v_log_f32_e32 v85, v85
	v_mul_f32_e64 v88, |v113|, s91
	v_exp_f32_e32 v88, v88
	v_mul_f32_e32 v99, 0x3db504f3, v90
	v_mfma_f32_32x32x16_bf16 v[64:79], v[104:107], v[152:155], v[64:79]
	v_max_f32_e32 v220, 0, v123
	v_min_f32_e32 v117, 0, v123
	v_mul_f32_e64 v90, |v99|, s91
	v_fmac_f32_e32 v220, 0x3f317218, v125
	v_cndmask_b32_e32 v182, 0, v183, vcc
	v_cmp_lt_i32_e32 vcc, 42, v217
	v_fmac_f32_e32 v117, 0xbf317218, v125
	v_max_f32_e32 v112, 0, v87
	v_min_f32_e32 v87, 0, v87
	v_exp_f32_e32 v104, v90
	v_cndmask_b32_e32 v116, 0, v220, vcc
	v_cndmask_b32_e32 v114, v202, v117, vcc
	v_cmp_lt_i32_e32 vcc, 43, v217
	v_fmac_f32_e32 v87, 0xbf317218, v85
	v_mul_f32_e32 v89, 0x3db504f3, v89
	v_fmac_f32_e32 v112, 0x3f317218, v85
	v_cndmask_b32_e32 v85, v202, v87, vcc
	v_add_f32_e32 v87, 1.0, v88
	v_mul_f32_e64 v88, |v89|, s91
	v_exp_f32_e32 v97, v88
	v_max_f32_e32 v98, 0, v89
	v_min_f32_e32 v108, 0, v89
	v_add_f32_e32 v89, 1.0, v104
	v_mul_f32_e32 v104, 0x3db504f3, v91
	v_mul_f32_e64 v91, |v104|, s91
	s_waitcnt lgkmcnt(0)
	v_mfma_f32_32x32x16_bf16 v[64:79], v[100:103], v[156:159], v[64:79]
	v_exp_f32_e32 v91, v91
	v_mul_f32_e32 v93, 0x3db504f3, v93
	v_mul_f32_e32 v103, 0x3db504f3, v94
	v_add_f32_e32 v97, 1.0, v97
	v_mul_f32_e64 v100, |v93|, s91
	v_mul_f32_e64 v94, |v103|, s91
	v_log_f32_e32 v90, v97
	v_max_f32_e32 v97, 0, v99
	v_min_f32_e32 v109, 0, v99
	v_max_f32_e32 v99, 0, v104
	v_min_f32_e32 v110, 0, v104
	v_exp_f32_e32 v102, v100
	v_exp_f32_e32 v104, v94
	v_log_f32_e32 v88, v87
	v_log_f32_e32 v89, v89
	v_add_f32_e32 v91, 1.0, v91
	v_mul_f32_e32 v101, 0x3db504f3, v92
	v_mul_f32_e64 v92, |v101|, s91
	v_log_f32_e32 v91, v91
	v_exp_f32_e32 v92, v92
	v_max_f32_e32 v100, 0, v101
	v_min_f32_e32 v111, 0, v101
	v_add_f32_e32 v101, 1.0, v102
	v_max_f32_e32 v102, 0, v93
	v_min_f32_e32 v115, 0, v93
	v_add_f32_e32 v93, 1.0, v104
	v_mul_f32_e32 v104, 0x3db504f3, v95
	v_max_f32_e32 v96, 0, v113
	v_mul_f32_e64 v95, |v104|, s91
	v_cndmask_b32_e32 v112, 0, v112, vcc
	v_min_f32_e32 v87, 0, v113
	v_log_f32_e32 v94, v101
	v_exp_f32_e32 v95, v95
	v_max_f32_e32 v101, 0, v103
	v_min_f32_e32 v117, 0, v103
	v_max_f32_e32 v103, 0, v104
	v_min_f32_e32 v118, 0, v104
	v_pk_mul_f32 v[104:105], v[88:89], s[94:95] op_sel_hi:[1,0]
	v_cmp_lt_i32_e32 vcc, 48, v217
	v_pk_fma_f32 v[88:89], v[88:89], s[94:95], v[96:97] op_sel_hi:[1,0,1]
	v_sub_f32_e32 v87, v87, v104
	v_pk_mul_f32 v[106:107], v[90:91], s[94:95] op_sel_hi:[1,0]
	v_cndmask_b32_e32 v96, 0, v88, vcc
	v_sub_f32_e32 v88, v109, v105
	v_add_f32_e32 v92, 1.0, v92
	v_cndmask_b32_e32 v87, v202, v87, vcc
	v_sub_f32_e32 v104, v108, v106
	v_cndmask_b32_e64 v97, 0, v89, s[10:11]
	v_cndmask_b32_e64 v108, v202, v88, s[10:11]
	v_pk_fma_f32 v[88:89], v[90:91], s[94:95], v[98:99] op_sel_hi:[1,0,1]
	v_cmp_lt_i32_e32 vcc, 51, v217
	v_log_f32_e32 v92, v92
	v_log_f32_e32 v93, v93
	v_cndmask_b32_e32 v91, 0, v89, vcc
	v_cndmask_b32_e64 v90, 0, v88, s[0:1]
	v_sub_f32_e32 v88, v110, v107
	v_add_f32_e32 v95, 1.0, v95
	v_cndmask_b32_e32 v107, v202, v88, vcc
	v_pk_add_f32 v[88:89], v[96:97], v[90:91]
	v_log_f32_e32 v95, v95
	v_pk_add_f32 v[88:89], v[88:89], v[88:89] op_sel:[0,1] op_sel_hi:[1,0]
	v_pk_mul_f32 v[98:99], v[92:93], s[94:95] op_sel_hi:[1,0]
	v_mov_b32_e32 v89, v88
	v_mov_b32_e32 v96, v88
	s_nop 1
	v_permlane32_swap_b32_e32 v89, v96
	v_cndmask_b32_e64 v113, v89, v96, s[4:5]
	v_sub_f32_e32 v89, v111, v98
	v_cmp_lt_i32_e32 vcc, 56, v217
	v_pk_fma_f32 v[92:93], v[92:93], s[94:95], v[100:101] op_sel_hi:[1,0,1]
	v_cndmask_b32_e64 v106, v202, v104, s[0:1]
	v_cndmask_b32_e32 v96, v202, v89, vcc
	v_pk_mul_f32 v[104:105], v[94:95], s[94:95] op_sel_hi:[1,0]
	v_cmp_lt_i32_e64 s[0:1], 57, v217
	v_cmp_lt_i32_e64 s[10:11], 58, v217
	v_cndmask_b32_e32 v92, 0, v92, vcc
	v_pk_fma_f32 v[94:95], v[94:95], s[94:95], v[102:103] op_sel_hi:[1,0,1]
	v_cmp_lt_i32_e32 vcc, 59, v217
	v_sub_f32_e32 v89, v115, v104
	v_cndmask_b32_e64 v93, 0, v93, s[10:11]
	v_cndmask_b32_e32 v95, 0, v95, vcc
	v_cndmask_b32_e64 v94, 0, v94, s[0:1]
	v_cndmask_b32_e64 v104, v202, v89, s[0:1]
	v_sub_f32_e32 v89, v117, v99
	v_pk_add_f32 v[98:99], v[92:93], v[94:95]
	v_cndmask_b32_e64 v100, v202, v89, s[10:11]
	v_sub_f32_e32 v89, v118, v105
	v_pk_add_f32 v[98:99], v[98:99], v[98:99] op_sel:[0,1] op_sel_hi:[1,0]
	v_cndmask_b32_e32 v101, v202, v89, vcc
	v_mov_b32_e32 v89, v98
	v_mov_b32_e32 v92, v98
	s_nop 1
	v_permlane32_swap_b32_e32 v89, v92
	v_cndmask_b32_e64 v183, v89, v92, s[4:5]
	v_mov_b32_e32 v177, v98
	v_mov_b32_e32 v117, v88
	v_pk_add_f32 v[98:99], v[176:177], v[182:183]
	v_pk_add_f32 v[88:89], v[116:117], v[112:113]
	v_mul_f32_e32 v64, 0x3db504f3, v64
	v_pk_add_f32 v[88:89], v[98:99], v[88:89]
	v_mul_f32_e32 v65, 0x3db504f3, v65
	v_mov_b32_e32 v92, v88
	v_mov_b32_e32 v98, v88
	s_nop 1
	v_permlane32_swap_b32_e32 v92, v98
	v_cndmask_b32_e64 v92, v92, v98, s[4:5]
	v_add_f32_e32 v109, v88, v92
	v_add_f32_e32 v88, v195, v89
	v_cndmask_b32_e64 v92, 0, v92, s[4:5]
	v_add_f32_e32 v88, v92, v88
	v_sub_f32_e32 v85, v85, v88
	v_mul_f32_e32 v85, 0x3fb8aa3b, v85
	v_exp_f32_e32 v115, v85
	v_add_f32_e32 v85, v112, v88
	v_sub_f32_e32 v88, v114, v85
	v_add_f32_e32 v85, v116, v85
	v_sub_f32_e32 v83, v83, v85
	v_mul_f32_e32 v83, 0x3fb8aa3b, v83
	v_exp_f32_e32 v114, v83
	v_add_f32_e32 v83, v182, v85
	v_sub_f32_e32 v81, v81, v83
	v_mul_f32_e32 v81, 0x3fb8aa3b, v81
	v_exp_f32_e32 v116, v81
	v_add_f32_e32 v81, v195, v99
	v_cndmask_b32_e64 v83, 0, v113, s[4:5]
	v_add_f32_e32 v81, v83, v81
	v_sub_f32_e32 v83, v107, v81
	v_mul_f32_e32 v83, 0x3fb8aa3b, v83
	v_add_f32_e32 v81, v91, v81
	v_exp_f32_e32 v107, v83
	v_sub_f32_e32 v83, v108, v81
	v_mul_f32_e32 v83, 0x3fb8aa3b, v83
	v_add_f32_e32 v81, v97, v81
	v_exp_f32_e32 v91, v83
	v_sub_f32_e32 v83, v106, v81
	v_add_f32_e32 v81, v90, v81
	v_sub_f32_e32 v81, v87, v81
	v_mul_f32_e32 v81, 0x3fb8aa3b, v81
	v_exp_f32_e32 v117, v81
	v_cndmask_b32_e64 v81, 0, v183, s[4:5]
	v_mul_f32_e32 v83, 0x3fb8aa3b, v83
	v_add_f32_e32 v81, v218, v81
	v_exp_f32_e32 v113, v83
	v_sub_f32_e32 v83, v101, v81
	v_mul_f32_e32 v83, 0x3fb8aa3b, v83
	v_add_f32_e32 v81, v81, v95
	v_exp_f32_e32 v118, v83
	v_sub_f32_e32 v83, v100, v81
	v_mul_f32_e32 v83, 0x3fb8aa3b, v83
	v_add_f32_e32 v81, v93, v81
	v_exp_f32_e32 v95, v83
	v_sub_f32_e32 v83, v104, v81
	v_mul_f32_e32 v83, 0x3fb8aa3b, v83
	v_exp_f32_e32 v93, v83
	v_mul_f32_e64 v83, |v64|, s91
	v_exp_f32_e32 v83, v83
	v_add_f32_e32 v81, v94, v81
	v_sub_f32_e32 v81, v96, v81
	v_mul_f32_e32 v81, 0x3fb8aa3b, v81
	v_exp_f32_e32 v119, v81
	v_add_f32_e32 v81, 1.0, v83
	v_mul_f32_e64 v83, |v65|, s91
	v_mul_f32_e32 v66, 0x3db504f3, v66
	v_exp_f32_e32 v83, v83
	v_log_f32_e32 v127, v81
	v_mul_f32_e64 v81, |v66|, s91
	v_exp_f32_e32 v81, v81
	v_max_f32_e32 v87, 0, v64
	v_min_f32_e32 v176, 0, v64
	v_add_f32_e32 v64, 1.0, v83
	v_log_f32_e32 v125, v64
	v_add_f32_e32 v64, 1.0, v81
	v_log_f32_e32 v123, v64
	v_mul_f32_e32 v64, 0x3db504f3, v67
	v_max_f32_e32 v85, 0, v65
	v_min_f32_e32 v177, 0, v65
	v_mul_f32_e64 v65, |v64|, s91
	v_mul_f32_e32 v67, 0x3db504f3, v68
	v_exp_f32_e32 v65, v65
	v_mul_f32_e64 v68, |v67|, s91
	v_exp_f32_e32 v68, v68
	v_max_f32_e32 v83, 0, v66
	v_add_f32_e32 v65, 1.0, v65
	v_min_f32_e32 v182, 0, v66
	v_log_f32_e32 v121, v65
	v_add_f32_e32 v65, 1.0, v68
	v_mul_f32_e32 v66, 0x3db504f3, v69
	v_log_f32_e32 v65, v65
	v_mul_f32_e64 v68, |v66|, s91
	v_exp_f32_e32 v68, v68
	v_max_f32_e32 v81, 0, v64
	v_min_f32_e32 v183, 0, v64
	v_max_f32_e32 v64, 0, v67
	v_fmac_f32_e32 v64, 0x3f317218, v65
	v_cmp_lt_i32_e32 vcc, 8, v217
	v_mul_f32_e32 v88, 0x3fb8aa3b, v88
	v_exp_f32_e32 v112, v88
	v_cndmask_b32_e32 v94, 0, v64, vcc
	v_min_f32_e32 v64, 0, v67
	v_add_f32_e32 v67, 1.0, v68
	v_log_f32_e32 v67, v67
	v_fmac_f32_e32 v64, 0xbf317218, v65
	v_mul_f32_e32 v65, 0x3db504f3, v70
	v_mul_f32_e64 v68, |v65|, s91
	v_exp_f32_e32 v68, v68
	v_cndmask_b32_e32 v218, v202, v64, vcc
	v_max_f32_e32 v64, 0, v66
	v_fmac_f32_e32 v64, 0x3f317218, v67
	v_cmp_lt_i32_e32 vcc, 9, v217
	v_mul_f32_e32 v69, 0x3db504f3, v74
	v_mul_f32_e32 v74, 0x3db504f3, v75
	v_cndmask_b32_e32 v88, 0, v64, vcc
	v_min_f32_e32 v64, 0, v66
	v_add_f32_e32 v66, 1.0, v68
	v_fmac_f32_e32 v64, 0xbf317218, v67
	v_mul_f32_e32 v67, 0x3db504f3, v71
	v_log_f32_e32 v66, v66
	v_mul_f32_e64 v68, |v67|, s91
	v_exp_f32_e32 v68, v68
	v_cndmask_b32_e32 v219, v202, v64, vcc
	v_max_f32_e32 v64, 0, v65
	v_fmac_f32_e32 v64, 0x3f317218, v66
	v_cmp_lt_i32_e32 vcc, 10, v217
	v_mul_f32_e32 v75, 0x3db504f3, v76
	v_min_f32_e32 v102, 0, v69
	v_cndmask_b32_e32 v92, 0, v64, vcc
	v_min_f32_e32 v64, 0, v65
	v_add_f32_e32 v65, 1.0, v68
	v_log_f32_e32 v65, v65
	v_fmac_f32_e32 v64, 0xbf317218, v66
	v_cndmask_b32_e32 v220, v202, v64, vcc
	v_max_f32_e32 v64, 0, v67
	v_min_f32_e32 v66, 0, v67
	v_fmac_f32_e32 v64, 0x3f317218, v65
	v_cmp_lt_i32_e32 vcc, 11, v217
	v_fmac_f32_e32 v66, 0xbf317218, v65
	v_mul_f32_e32 v65, 0x3db504f3, v73
	v_cndmask_b32_e32 v221, v202, v66, vcc
	v_mul_f32_e64 v66, |v65|, s91
	v_mul_f32_e32 v68, 0x3db504f3, v72
	v_exp_f32_e32 v67, v66
	v_cndmask_b32_e32 v90, 0, v64, vcc
	v_mul_f32_e64 v64, |v68|, s91
	v_max_f32_e32 v66, 0, v68
	v_min_f32_e32 v72, 0, v68
	v_mul_f32_e64 v68, |v69|, s91
	v_exp_f32_e32 v71, v68
	v_add_f32_e32 v67, 1.0, v67
	v_log_f32_e32 v68, v67
	v_mul_f32_e64 v67, |v74|, s91
	v_max_f32_e32 v70, 0, v65
	v_min_f32_e32 v73, 0, v65
	v_add_f32_e32 v65, 1.0, v71
	v_exp_f32_e32 v71, v67
	v_max_f32_e32 v67, 0, v69
	v_mul_f32_e32 v77, 0x3db504f3, v77
	v_exp_f32_e32 v64, v64
	v_add_f32_e32 v69, 1.0, v71
	v_mul_f32_e64 v71, |v75|, s91
	v_exp_f32_e32 v76, v71
	v_max_f32_e32 v71, 0, v74
	v_min_f32_e32 v103, 0, v74
	v_mul_f32_e32 v97, 0x3db504f3, v78
	v_add_f32_e32 v74, 1.0, v76
	v_mul_f32_e64 v76, |v77|, s91
	v_exp_f32_e32 v96, v76
	v_mul_f32_e64 v78, |v97|, s91
	v_exp_f32_e32 v98, v78
	v_add_f32_e32 v64, 1.0, v64
	v_log_f32_e32 v64, v64
	v_log_f32_e32 v65, v65
	v_max_f32_e32 v76, 0, v75
	v_min_f32_e32 v104, 0, v75
	v_add_f32_e32 v75, 1.0, v96
	v_log_f32_e32 v69, v69
	v_log_f32_e32 v78, v75
	v_add_f32_e32 v75, 1.0, v98
	v_mul_f32_e32 v98, 0x3db504f3, v79
	v_max_f32_e32 v96, 0, v77
	v_min_f32_e32 v105, 0, v77
	v_mul_f32_e64 v77, |v98|, s91
	v_exp_f32_e32 v79, v77
	v_max_f32_e32 v77, 0, v97
	v_min_f32_e32 v106, 0, v97
	v_max_f32_e32 v97, 0, v98
	v_min_f32_e32 v108, 0, v98
	v_pk_mul_f32 v[98:99], v[64:65], s[94:95] op_sel_hi:[1,0]
	v_cmp_lt_i32_e32 vcc, 16, v217
	v_sub_f32_e32 v72, v72, v98
	v_pk_mul_f32 v[100:101], v[68:69], s[94:95] op_sel_hi:[1,0]
	v_cndmask_b32_e32 v222, v202, v72, vcc
	v_sub_f32_e32 v72, v73, v100
	v_cmp_lt_i32_e64 s[0:1], 17, v217
	v_pk_fma_f32 v[64:65], v[64:65], s[94:95], v[66:67] op_sel_hi:[1,0,1]
	v_log_f32_e32 v74, v74
	v_log_f32_e32 v75, v75
	v_add_f32_e32 v79, 1.0, v79
	v_cndmask_b32_e64 v223, v202, v72, s[0:1]
	v_cmp_lt_i32_e64 s[10:11], 18, v217
	v_cndmask_b32_e32 v72, 0, v64, vcc
	v_sub_f32_e32 v64, v102, v99
	v_log_f32_e32 v79, v79
	v_cndmask_b32_e64 v73, 0, v65, s[10:11]
	v_cndmask_b32_e64 v224, v202, v64, s[10:11]
	v_pk_fma_f32 v[64:65], v[68:69], s[94:95], v[70:71] op_sel_hi:[1,0,1]
	v_cmp_lt_i32_e32 vcc, 19, v217
	v_cndmask_b32_e64 v98, 0, v64, s[0:1]
	v_sub_f32_e32 v64, v103, v101
	v_cndmask_b32_e32 v99, 0, v65, vcc
	v_exp_f32_e32 v120, v120
	v_cndmask_b32_e32 v225, v202, v64, vcc
	v_pk_add_f32 v[64:65], v[72:73], v[98:99]
	v_cmp_lt_i32_e32 vcc, 24, v217
	v_pk_add_f32 v[100:101], v[64:65], v[64:65] op_sel:[0,1] op_sel_hi:[1,0]
	v_pk_mul_f32 v[64:65], v[74:75], s[94:95] op_sel_hi:[1,0]
	v_pk_mul_f32 v[66:67], v[78:79], s[94:95] op_sel_hi:[1,0]
	v_sub_f32_e32 v64, v104, v64
	v_log_f32_e32 v124, v124
	v_cndmask_b32_e32 v72, v202, v64, vcc
	v_sub_f32_e32 v64, v105, v66
	v_cmp_lt_i32_e64 s[0:1], 25, v217
	v_add_f32_e32 v120, 1.0, v120
	v_cmp_lt_i32_e64 s[10:11], 26, v217
	v_cndmask_b32_e64 v101, v202, v64, s[0:1]
	v_sub_f32_e32 v64, v106, v65
	v_log_f32_e32 v120, v120
	v_pk_fma_f32 v[68:69], v[74:75], s[94:95], v[76:77] op_sel_hi:[1,0,1]
	v_cndmask_b32_e64 v226, v202, v64, s[10:11]
	v_pk_fma_f32 v[64:65], v[78:79], s[94:95], v[96:97] op_sel_hi:[1,0,1]
	v_cndmask_b32_e32 v74, 0, v68, vcc
	v_cmp_lt_i32_e32 vcc, 27, v217
	v_cndmask_b32_e64 v76, 0, v64, s[0:1]
	v_sub_f32_e32 v64, v108, v67
	v_pk_mul_f32 v[78:79], v[126:127], s[94:95] op_sel_hi:[1,0]
	v_cndmask_b32_e32 v227, v202, v64, vcc
	v_sub_f32_e32 v64, v181, v78
	v_cmp_lt_i32_e64 s[0:1], 32, v217
	v_pk_mul_f32 v[96:97], v[124:125], s[94:95] op_sel_hi:[1,0]
	v_cndmask_b32_e64 v75, 0, v69, s[10:11]
	v_cndmask_b32_e64 v68, v202, v64, s[0:1]
	v_sub_f32_e32 v64, v180, v96
	v_cmp_lt_i32_e64 s[10:11], 33, v217
	v_pk_mul_f32 v[102:103], v[122:123], s[94:95] op_sel_hi:[1,0]
	v_pk_mul_f32 v[104:105], v[120:121], s[94:95] op_sel_hi:[1,0]
	v_cndmask_b32_e64 v69, v202, v64, s[10:11]
	v_sub_f32_e32 v64, v179, v102
	v_cndmask_b32_e64 v70, v202, v64, s[12:13]
	v_sub_f32_e32 v64, v178, v104
	v_cndmask_b32_e32 v77, 0, v65, vcc
	v_cndmask_b32_e64 v71, v202, v64, s[14:15]
	v_pk_fma_f32 v[64:65], v[126:127], s[94:95], v[86:87] op_sel_hi:[1,0,1]
	v_pk_fma_f32 v[66:67], v[124:125], s[94:95], v[84:85] op_sel_hi:[1,0,1]
	v_cndmask_b32_e64 v64, 0, v64, s[0:1]
	v_cmp_lt_i32_e64 s[0:1], 1, v217
	v_cndmask_b32_e64 v84, 0, v66, s[10:11]
	v_cmp_lt_i32_e64 s[10:11], 2, v217
	v_cndmask_b32_e64 v85, 0, v67, s[0:1]
	v_pk_fma_f32 v[66:67], v[122:123], s[94:95], v[82:83] op_sel_hi:[1,0,1]
	v_cmp_lt_i32_e32 vcc, 0, v217
	v_cndmask_b32_e64 v83, 0, v67, s[10:11]
	v_cndmask_b32_e64 v82, 0, v66, s[12:13]
	v_pk_fma_f32 v[66:67], v[120:121], s[94:95], v[80:81] op_sel_hi:[1,0,1]
	v_cmp_lt_i32_e64 s[12:13], 3, v217
	v_cndmask_b32_e32 v65, 0, v65, vcc
	v_cndmask_b32_e64 v80, 0, v66, s[14:15]
	v_cndmask_b32_e64 v81, 0, v67, s[12:13]
	v_pk_add_f32 v[64:65], v[64:65], v[84:85]
	v_pk_add_f32 v[66:67], v[82:83], v[80:81]
	v_add_f32_e32 v108, v109, v89
	v_pk_add_f32 v[86:87], v[64:65], v[66:67]
	v_sub_f32_e32 v79, v176, v79
	v_mov_b32_e32 v64, v86
	v_mov_b32_e32 v65, v86
	s_nop 1
	v_permlane32_swap_b32_e32 v64, v65
	v_cndmask_b32_e64 v106, v64, v65, s[4:5]
	v_add_f32_e32 v64, v195, v108
	v_cndmask_b32_e64 v65, 0, v106, s[4:5]
	v_add_f32_e32 v64, v65, v64
	v_sub_f32_e32 v65, v71, v64
	v_mul_f32_e32 v65, 0x3fb8aa3b, v65
	v_add_f32_e32 v64, v80, v64
	v_exp_f32_e32 v66, v65
	v_sub_f32_e32 v65, v70, v64
	v_add_f32_e32 v64, v82, v64
	v_sub_f32_e32 v67, v69, v64
	v_add_f32_e32 v64, v84, v64
	v_sub_f32_e32 v64, v68, v64
	v_mul_f32_e32 v65, 0x3fb8aa3b, v65
	v_mul_f32_e32 v64, 0x3fb8aa3b, v64
	v_mul_f32_e32 v67, 0x3fb8aa3b, v67
	v_exp_f32_e32 v68, v64
	v_exp_f32_e32 v69, v65
	v_pk_add_f32 v[64:65], v[74:75], v[76:77]
	v_mov_b32_e32 v74, v87
	v_mov_b32_e32 v78, v87
	v_exp_f32_e32 v67, v67
	s_nop 0
	v_permlane32_swap_b32_e32 v74, v78
	v_pk_add_f32 v[110:111], v[64:65], v[64:65] op_sel:[0,1] op_sel_hi:[1,0]
	v_cvt_pk_bf16_f32 v64, v68, v67
	v_cvt_pk_bf16_f32 v65, v69, v66
	v_cvt_pk_bf16_f32 v66, v116, v114
	v_cvt_pk_bf16_f32 v67, v112, v115
	v_cvt_pk_bf16_f32 v68, v117, v113
	v_cvt_pk_bf16_f32 v69, v91, v107
	v_cndmask_b32_e64 v107, v74, v78, s[4:5]
	v_mov_b32_e32 v74, v100
	v_mov_b32_e32 v78, v100
	s_nop 1
	v_permlane32_swap_b32_e32 v74, v78
	v_cndmask_b32_e64 v89, v74, v78, s[4:5]
	v_mov_b32_e32 v74, v110
	v_mov_b32_e32 v78, v110
	s_nop 1
	v_permlane32_swap_b32_e32 v74, v78
	v_cvt_pk_bf16_f32 v70, v119, v93
	v_cvt_pk_bf16_f32 v71, v95, v118
	v_cndmask_b32_e64 v91, v74, v78, s[4:5]
	v_mov_b32_e32 v93, v110
	v_mov_b32_e32 v95, v100
	v_pk_add_f32 v[110:111], v[92:93], v[90:91]
	v_pk_add_f32 v[94:95], v[94:95], v[88:89]
	v_pk_add_f32 v[86:87], v[86:87], v[106:107]
	v_pk_add_f32 v[94:95], v[94:95], v[110:111]
	v_sub_f32_e32 v82, v182, v103
	v_mov_b32_e32 v74, v94
	v_mov_b32_e32 v78, v94
	s_nop 1
	v_permlane32_swap_b32_e32 v74, v78
	v_cndmask_b32_e64 v74, v74, v78, s[4:5]
	v_add_f32_e32 v78, v94, v74
	v_add_f32_e32 v109, v78, v95
	v_pk_add_f32 v[86:87], v[86:87], v[108:109]
	v_cndmask_b32_e64 v94, 0, v107, s[4:5]
	v_add_f32_e32 v78, v195, v86
	v_add_f32_e32 v93, v78, v109
	v_add_f32_e32 v93, v94, v93
	v_sub_f32_e32 v80, v177, v97
	v_cndmask_b32_e64 v82, v202, v82, s[10:11]
	v_add_f32_e32 v81, v81, v93
	v_cndmask_b32_e64 v80, v202, v80, s[0:1]
	v_sub_f32_e32 v82, v82, v81
	v_add_f32_e32 v81, v83, v81
	v_cndmask_b32_e32 v79, v202, v79, vcc
	v_sub_f32_e32 v80, v80, v81
	v_add_f32_e32 v81, v85, v81
	v_sub_f32_e32 v79, v79, v81
	v_add_f32_e32 v81, v78, v95
	v_cndmask_b32_e64 v74, 0, v74, s[4:5]
	v_add_f32_e32 v74, v74, v81
	v_sub_f32_e32 v81, v221, v74
	v_add_f32_e32 v74, v90, v74
	v_sub_f32_e32 v83, v220, v74
	v_add_f32_e32 v74, v92, v74
	v_sub_f32_e32 v85, v219, v74
	v_add_f32_e32 v74, v88, v74
	v_add_f32_e32 v88, v78, v111
	v_cndmask_b32_e64 v89, 0, v89, s[4:5]
	v_add_f32_e32 v88, v89, v88
	v_sub_f32_e32 v89, v225, v88
	v_add_f32_e32 v88, v99, v88
	v_add_f32_e32 v73, v73, v88
	v_sub_f32_e32 v90, v224, v88
	v_sub_f32_e32 v88, v223, v73
	v_add_f32_e32 v73, v98, v73
	v_sub_f32_e32 v73, v222, v73
	v_mul_f32_e32 v73, 0x3fb8aa3b, v73
	v_exp_f32_e32 v92, v73
	v_add_f32_e32 v73, 0, v78
	v_cndmask_b32_e64 v78, 0, v91, s[4:5]
	v_add_f32_e32 v73, v73, v78
	v_sub_f32_e32 v78, v227, v73
	v_add_f32_e32 v73, v77, v73
	v_sub_f32_e32 v84, v183, v105
	v_sub_f32_e32 v77, v226, v73
	v_add_f32_e32 v73, v75, v73
	v_cndmask_b32_e64 v84, v202, v84, s[12:13]
	v_sub_f32_e32 v75, v101, v73
	v_add_f32_e32 v73, v76, v73
	v_sub_f32_e32 v84, v84, v93
	v_sub_f32_e32 v72, v72, v73
	v_mul_f32_e32 v84, 0x3fb8aa3b, v84
	v_mul_f32_e32 v82, 0x3fb8aa3b, v82
	v_mul_f32_e32 v80, 0x3fb8aa3b, v80
	v_mul_f32_e32 v81, 0x3fb8aa3b, v81
	v_mul_f32_e32 v83, 0x3fb8aa3b, v83
	v_mul_f32_e32 v85, 0x3fb8aa3b, v85
	v_sub_f32_e32 v74, v218, v74
	v_mul_f32_e32 v89, 0x3fb8aa3b, v89
	v_mul_f32_e32 v90, 0x3fb8aa3b, v90
	v_mul_f32_e32 v88, 0x3fb8aa3b, v88
	v_mul_f32_e32 v78, 0x3fb8aa3b, v78
	v_mul_f32_e32 v77, 0x3fb8aa3b, v77
	v_mul_f32_e32 v72, 0x3fb8aa3b, v72
	v_exp_f32_e32 v84, v84
	v_exp_f32_e32 v82, v82
	v_exp_f32_e32 v80, v80
	v_mul_f32_e32 v79, 0x3fb8aa3b, v79
	v_exp_f32_e32 v81, v81
	v_exp_f32_e32 v83, v83
	v_exp_f32_e32 v85, v85
	v_mul_f32_e32 v74, 0x3fb8aa3b, v74
	v_exp_f32_e32 v89, v89
	v_exp_f32_e32 v90, v90
	v_exp_f32_e32 v88, v88
	v_exp_f32_e32 v91, v78
	v_exp_f32_e32 v93, v77
	v_mul_f32_e32 v75, 0x3fb8aa3b, v75
	v_exp_f32_e32 v94, v72
	v_exp_f32_e32 v79, v79
	v_exp_f32_e32 v74, v74
	v_exp_f32_e32 v78, v75
	v_cvt_pk_bf16_f32 v72, v79, v80
	v_cvt_pk_bf16_f32 v73, v82, v84
	v_cvt_pk_bf16_f32 v74, v74, v85
	v_cvt_pk_bf16_f32 v75, v83, v81
	v_cvt_pk_bf16_f32 v76, v92, v88
	v_cvt_pk_bf16_f32 v77, v90, v89
	v_cvt_pk_bf16_f32 v78, v94, v78
	v_cvt_pk_bf16_f32 v79, v93, v91
	v_permlane32_swap_b32_e32 v64, v66
	v_permlane32_swap_b32_e32 v65, v67
	v_permlane32_swap_b32_e32 v68, v70
	v_permlane32_swap_b32_e32 v69, v71
	v_permlane32_swap_b32_e32 v72, v74
	v_permlane32_swap_b32_e32 v73, v75
	v_permlane32_swap_b32_e32 v76, v78
	v_permlane32_swap_b32_e32 v77, v79
	v_add_f32_e32 v219, v86, v87
	ds_read_b64_tr_b16 v[80:81], v207 offset:0
	ds_read_b64_tr_b16 v[82:83], v207 offset:0x800
	ds_read_b64_tr_b16 v[84:85], v207 offset:0x1000
	ds_read_b64_tr_b16 v[86:87], v207 offset:0x1800
	ds_read_b64_tr_b16 v[88:89], v207 offset:0x2000
	ds_read_b64_tr_b16 v[90:91], v207 offset:0x2800
	ds_read_b64_tr_b16 v[92:93], v207 offset:0x3000
	ds_read_b64_tr_b16 v[94:95], v207 offset:0x3800
	s_waitcnt lgkmcnt(0)
	s_nop 0
	v_mfma_f32_32x32x16_bf16 v[48:63], v[72:75], v[80:83], v[48:63]
	ds_read_b64_tr_b16 v[80:81], v207 offset:0x200
	ds_read_b64_tr_b16 v[82:83], v207 offset:0xa00
	v_mfma_f32_32x32x16_bf16 v[48:63], v[76:79], v[84:87], v[48:63]
	ds_read_b64_tr_b16 v[84:85], v207 offset:0x1200
	ds_read_b64_tr_b16 v[86:87], v207 offset:0x1a00
	v_mfma_f32_32x32x16_bf16 v[48:63], v[64:67], v[88:91], v[48:63]
	ds_read_b64_tr_b16 v[88:89], v207 offset:0x2200
	ds_read_b64_tr_b16 v[90:91], v207 offset:0x2a00
	v_mfma_f32_32x32x16_bf16 v[48:63], v[68:71], v[92:95], v[48:63]
	ds_read_b64_tr_b16 v[92:93], v207 offset:0x3200
	ds_read_b64_tr_b16 v[94:95], v207 offset:0x3a00
	s_waitcnt lgkmcnt(0)
	v_mfma_f32_32x32x16_bf16 v[32:47], v[72:75], v[80:83], v[32:47]
	ds_read_b64_tr_b16 v[80:81], v207 offset:0x400
	ds_read_b64_tr_b16 v[82:83], v207 offset:0xc00
	v_mfma_f32_32x32x16_bf16 v[32:47], v[76:79], v[84:87], v[32:47]
	ds_read_b64_tr_b16 v[84:85], v207 offset:0x1400
	ds_read_b64_tr_b16 v[86:87], v207 offset:0x1c00
	v_mfma_f32_32x32x16_bf16 v[32:47], v[64:67], v[88:91], v[32:47]
	ds_read_b64_tr_b16 v[88:89], v207 offset:0x2400
	ds_read_b64_tr_b16 v[90:91], v207 offset:0x2c00
	v_mfma_f32_32x32x16_bf16 v[32:47], v[68:71], v[92:95], v[32:47]
	ds_read_b64_tr_b16 v[92:93], v207 offset:0x3400
	ds_read_b64_tr_b16 v[94:95], v207 offset:0x3c00
	s_waitcnt lgkmcnt(0)
	v_mfma_f32_32x32x16_bf16 v[16:31], v[72:75], v[80:83], v[16:31]
	ds_read_b64_tr_b16 v[80:81], v207 offset:0x600
	ds_read_b64_tr_b16 v[82:83], v207 offset:0xe00
	v_mfma_f32_32x32x16_bf16 v[16:31], v[76:79], v[84:87], v[16:31]
	ds_read_b64_tr_b16 v[84:85], v207 offset:0x1600
	ds_read_b64_tr_b16 v[86:87], v207 offset:0x1e00
	v_mfma_f32_32x32x16_bf16 v[16:31], v[64:67], v[88:91], v[16:31]
	ds_read_b64_tr_b16 v[88:89], v207 offset:0x2600
	ds_read_b64_tr_b16 v[90:91], v207 offset:0x2e00
	v_mfma_f32_32x32x16_bf16 v[16:31], v[68:71], v[92:95], v[16:31]
	ds_read_b64_tr_b16 v[92:93], v207 offset:0x3600
	ds_read_b64_tr_b16 v[94:95], v207 offset:0x3e00
	s_waitcnt lgkmcnt(0)
	v_mfma_f32_32x32x16_bf16 v[0:15], v[72:75], v[80:83], v[0:15]
	s_nop 10
	v_mov_b64_e32 v[110:111], v[30:31]
	v_mov_b64_e32 v[108:109], v[28:29]
	v_mov_b64_e32 v[106:107], v[26:27]
	v_mov_b64_e32 v[104:105], v[24:25]
	v_mov_b64_e32 v[102:103], v[22:23]
	v_mov_b64_e32 v[100:101], v[20:21]
	v_mov_b64_e32 v[98:99], v[18:19]
	v_mfma_f32_32x32x16_bf16 v[0:15], v[76:79], v[84:87], v[0:15]
	v_mov_b64_e32 v[96:97], v[16:17]
	v_mfma_f32_32x32x16_bf16 v[0:15], v[64:67], v[88:91], v[0:15]
	v_mfma_f32_32x32x16_bf16 v[0:15], v[68:71], v[92:95], v[0:15]
	v_mov_b64_e32 v[94:95], v[46:47]
	v_mov_b64_e32 v[78:79], v[62:63]
	v_mov_b64_e32 v[92:93], v[44:45]
	v_mov_b64_e32 v[90:91], v[42:43]
	v_mov_b64_e32 v[88:89], v[40:41]
	v_mov_b64_e32 v[86:87], v[38:39]
	v_mov_b64_e32 v[84:85], v[36:37]
	s_nop 4
	v_mov_b64_e32 v[126:127], v[14:15]
	v_mov_b64_e32 v[82:83], v[34:35]
	v_mov_b64_e32 v[80:81], v[32:33]
	v_mov_b64_e32 v[124:125], v[12:13]
	v_mov_b64_e32 v[122:123], v[10:11]
	v_mov_b64_e32 v[120:121], v[8:9]
	v_mov_b64_e32 v[118:119], v[6:7]
	v_mov_b64_e32 v[116:117], v[4:5]
	v_mov_b64_e32 v[114:115], v[2:3]
	v_mov_b64_e32 v[112:113], v[0:1]
	v_mov_b64_e32 v[76:77], v[60:61]
	v_mov_b64_e32 v[74:75], v[58:59]
	v_mov_b64_e32 v[72:73], v[56:57]
	v_mov_b64_e32 v[70:71], v[54:55]
	v_mov_b64_e32 v[68:69], v[52:53]
	v_mov_b64_e32 v[66:67], v[50:51]
	v_mov_b64_e32 v[64:65], v[48:49]

.LBB0_677:
	s_or_b64 exec, exec, s[2:3]
	s_add_i32 s2, s10, 0x80
	s_ashr_i32 s3, s2, 31
	s_ashr_i32 s13, s0, 31
	s_mov_b32 s12, s0
	s_ashr_i32 s11, s10, 31
	s_lshl_b64 s[2:3], s[2:3], 12
	s_lshl_b64 s[8:9], s[12:13], 12
	s_lshl_b64 s[14:15], s[10:11], 12
	s_add_u32 s8, s38, s8
	s_addc_u32 s9, s39, s9
	s_add_u32 s14, s38, s14
	s_addc_u32 s15, s39, s15
	s_add_u32 s16, s38, s2
	v_mov_b32_e32 v0, 0
	s_addc_u32 s17, s39, s3
	s_mov_b32 s1, -2
	v_mov_b32_e32 v1, v0
	v_mov_b32_e32 v2, v0
	v_mov_b32_e32 v3, v0
	v_mov_b32_e32 v4, v0
	v_mov_b32_e32 v5, v0
	v_mov_b32_e32 v6, v0
	v_mov_b32_e32 v7, v0
	v_mov_b32_e32 v8, v0
	v_mov_b32_e32 v9, v0
	v_mov_b32_e32 v10, v0
	v_mov_b32_e32 v11, v0
	v_mov_b32_e32 v12, v0
	v_mov_b32_e32 v13, v0
	v_mov_b32_e32 v14, v0
	v_mov_b32_e32 v15, v0
	v_mov_b32_e32 v16, v0
	v_mov_b32_e32 v17, v0
	v_mov_b32_e32 v18, v0
	v_mov_b32_e32 v19, v0
	v_mov_b32_e32 v20, v0
	v_mov_b32_e32 v21, v0
	v_mov_b32_e32 v22, v0
	v_mov_b32_e32 v23, v0
	v_mov_b32_e32 v24, v0
	v_mov_b32_e32 v25, v0
	v_mov_b32_e32 v26, v0
	v_mov_b32_e32 v27, v0
	v_mov_b32_e32 v28, v0
	v_mov_b32_e32 v29, v0
	v_mov_b32_e32 v30, v0
	v_mov_b32_e32 v31, v0
	v_mov_b32_e32 v32, v0
	v_mov_b32_e32 v33, v0
	v_mov_b32_e32 v34, v0
	v_mov_b32_e32 v35, v0
	v_mov_b32_e32 v36, v0
	v_mov_b32_e32 v37, v0
	v_mov_b32_e32 v38, v0
	v_mov_b32_e32 v39, v0
	v_mov_b32_e32 v40, v0
	v_mov_b32_e32 v41, v0
	v_mov_b32_e32 v42, v0
	v_mov_b32_e32 v43, v0
	v_mov_b32_e32 v44, v0
	v_mov_b32_e32 v45, v0
	v_mov_b32_e32 v46, v0
	v_mov_b32_e32 v47, v0
	v_mov_b32_e32 v48, v0
	v_mov_b32_e32 v49, v0
	v_mov_b32_e32 v50, v0
	v_mov_b32_e32 v51, v0
	v_mov_b32_e32 v52, v0
	v_mov_b32_e32 v53, v0
	v_mov_b32_e32 v54, v0
	v_mov_b32_e32 v55, v0
	v_mov_b32_e32 v56, v0
	v_mov_b32_e32 v57, v0
	v_mov_b32_e32 v58, v0
	v_mov_b32_e32 v59, v0
	v_mov_b32_e32 v60, v0
	v_mov_b32_e32 v61, v0
	v_mov_b32_e32 v62, v0
	v_mov_b32_e32 v63, v0
	v_mov_b32_e32 v64, v0
	v_mov_b32_e32 v65, v0
	v_mov_b32_e32 v66, v0
	v_mov_b32_e32 v67, v0
	v_mov_b32_e32 v68, v0
	v_mov_b32_e32 v69, v0
	v_mov_b32_e32 v70, v0
	v_mov_b32_e32 v71, v0
	v_mov_b32_e32 v72, v0
	v_mov_b32_e32 v73, v0
	v_mov_b32_e32 v74, v0
	v_mov_b32_e32 v75, v0
	v_mov_b32_e32 v76, v0
	v_mov_b32_e32 v77, v0
	v_mov_b32_e32 v78, v0
	v_mov_b32_e32 v79, v0
	v_mov_b32_e32 v80, v0
	v_mov_b32_e32 v81, v0
	v_mov_b32_e32 v82, v0
	v_mov_b32_e32 v83, v0
	v_mov_b32_e32 v84, v0
	v_mov_b32_e32 v85, v0
	v_mov_b32_e32 v86, v0
	v_mov_b32_e32 v87, v0
	v_mov_b32_e32 v88, v0
	v_mov_b32_e32 v89, v0
	v_mov_b32_e32 v90, v0
	v_mov_b32_e32 v91, v0
	v_mov_b32_e32 v92, v0
	v_mov_b32_e32 v93, v0
	v_mov_b32_e32 v94, v0
	v_mov_b32_e32 v95, v0
	v_mov_b32_e32 v96, v0
	v_mov_b32_e32 v97, v0
	v_mov_b32_e32 v98, v0
	v_mov_b32_e32 v99, v0
	v_mov_b32_e32 v100, v0
	v_mov_b32_e32 v101, v0
	v_mov_b32_e32 v102, v0
	v_mov_b32_e32 v103, v0
	v_mov_b32_e32 v104, v0
	v_mov_b32_e32 v105, v0
	v_mov_b32_e32 v106, v0
	v_mov_b32_e32 v107, v0
	v_mov_b32_e32 v108, v0
	v_mov_b32_e32 v109, v0
	v_mov_b32_e32 v110, v0
	v_mov_b32_e32 v111, v0
	v_mov_b32_e32 v112, v0
	v_mov_b32_e32 v113, v0
	v_mov_b32_e32 v114, v0
	v_mov_b32_e32 v115, v0
	v_mov_b32_e32 v116, v0
	v_mov_b32_e32 v117, v0
	v_mov_b32_e32 v118, v0
	v_mov_b32_e32 v119, v0
	v_mov_b32_e32 v120, v0
	v_mov_b32_e32 v121, v0
	v_mov_b32_e32 v122, v0
	v_mov_b32_e32 v123, v0
	v_mov_b32_e32 v124, v0
	v_mov_b32_e32 v125, v0
	v_mov_b32_e32 v126, v0
	v_mov_b32_e32 v127, v0
	s_mov_b64 s[22:23], 0x34000100
	s_mov_b64 s[24:25], 0x34040100
	s_barrier
	s_barrier
	.p2align 6

.LBB0_765:
	s_or_b64 exec, exec, s[14:15]
	s_add_i32 s14, s12, 0x80
	s_ashr_i32 s15, s14, 31
	s_lshl_b64 s[16:17], s[14:15], 12
	s_ashr_i32 s15, s10, 31
	s_mov_b32 s14, s10
	s_ashr_i32 s13, s12, 31
	s_lshl_b64 s[18:19], s[14:15], 12
	s_lshl_b64 s[20:21], s[12:13], 12
	s_add_u32 s18, s26, s18
	s_addc_u32 s19, s27, s19
	s_add_u32 s20, s38, s20
	s_addc_u32 s21, s39, s21
	s_add_u32 s22, s38, s16
	v_mov_b32_e32 v0, 0
	s_addc_u32 s23, s39, s17
	s_mov_b32 s11, -2
	v_mov_b32_e32 v1, v0
	v_mov_b32_e32 v2, v0
	v_mov_b32_e32 v3, v0
	v_mov_b32_e32 v4, v0
	v_mov_b32_e32 v5, v0
	v_mov_b32_e32 v6, v0
	v_mov_b32_e32 v7, v0
	v_mov_b32_e32 v8, v0
	v_mov_b32_e32 v9, v0
	v_mov_b32_e32 v10, v0
	v_mov_b32_e32 v11, v0
	v_mov_b32_e32 v12, v0
	v_mov_b32_e32 v13, v0
	v_mov_b32_e32 v14, v0
	v_mov_b32_e32 v15, v0
	v_mov_b32_e32 v16, v0
	v_mov_b32_e32 v17, v0
	v_mov_b32_e32 v18, v0
	v_mov_b32_e32 v19, v0
	v_mov_b32_e32 v20, v0
	v_mov_b32_e32 v21, v0
	v_mov_b32_e32 v22, v0
	v_mov_b32_e32 v23, v0
	v_mov_b32_e32 v24, v0
	v_mov_b32_e32 v25, v0
	v_mov_b32_e32 v26, v0
	v_mov_b32_e32 v27, v0
	v_mov_b32_e32 v28, v0
	v_mov_b32_e32 v29, v0
	v_mov_b32_e32 v30, v0
	v_mov_b32_e32 v31, v0
	v_mov_b32_e32 v32, v0
	v_mov_b32_e32 v33, v0
	v_mov_b32_e32 v34, v0
	v_mov_b32_e32 v35, v0
	v_mov_b32_e32 v36, v0
	v_mov_b32_e32 v37, v0
	v_mov_b32_e32 v38, v0
	v_mov_b32_e32 v39, v0
	v_mov_b32_e32 v40, v0
	v_mov_b32_e32 v41, v0
	v_mov_b32_e32 v42, v0
	v_mov_b32_e32 v43, v0
	v_mov_b32_e32 v44, v0
	v_mov_b32_e32 v45, v0
	v_mov_b32_e32 v46, v0
	v_mov_b32_e32 v47, v0
	v_mov_b32_e32 v48, v0
	v_mov_b32_e32 v49, v0
	v_mov_b32_e32 v50, v0
	v_mov_b32_e32 v51, v0
	v_mov_b32_e32 v52, v0
	v_mov_b32_e32 v53, v0
	v_mov_b32_e32 v54, v0
	v_mov_b32_e32 v55, v0
	v_mov_b32_e32 v56, v0
	v_mov_b32_e32 v57, v0
	v_mov_b32_e32 v58, v0
	v_mov_b32_e32 v59, v0
	v_mov_b32_e32 v60, v0
	v_mov_b32_e32 v61, v0
	v_mov_b32_e32 v62, v0
	v_mov_b32_e32 v63, v0
	v_mov_b32_e32 v64, v0
	v_mov_b32_e32 v65, v0
	v_mov_b32_e32 v66, v0
	v_mov_b32_e32 v67, v0
	v_mov_b32_e32 v68, v0
	v_mov_b32_e32 v69, v0
	v_mov_b32_e32 v70, v0
	v_mov_b32_e32 v71, v0
	v_mov_b32_e32 v72, v0
	v_mov_b32_e32 v73, v0
	v_mov_b32_e32 v74, v0
	v_mov_b32_e32 v75, v0
	v_mov_b32_e32 v76, v0
	v_mov_b32_e32 v77, v0
	v_mov_b32_e32 v78, v0
	v_mov_b32_e32 v79, v0
	v_mov_b32_e32 v80, v0
	v_mov_b32_e32 v81, v0
	v_mov_b32_e32 v82, v0
	v_mov_b32_e32 v83, v0
	v_mov_b32_e32 v84, v0
	v_mov_b32_e32 v85, v0
	v_mov_b32_e32 v86, v0
	v_mov_b32_e32 v87, v0
	v_mov_b32_e32 v88, v0
	v_mov_b32_e32 v89, v0
	v_mov_b32_e32 v90, v0
	v_mov_b32_e32 v91, v0
	v_mov_b32_e32 v92, v0
	v_mov_b32_e32 v93, v0
	v_mov_b32_e32 v94, v0
	v_mov_b32_e32 v95, v0
	v_mov_b32_e32 v96, v0
	v_mov_b32_e32 v97, v0
	v_mov_b32_e32 v98, v0
	v_mov_b32_e32 v99, v0
	v_mov_b32_e32 v100, v0
	v_mov_b32_e32 v101, v0
	v_mov_b32_e32 v102, v0
	v_mov_b32_e32 v103, v0
	v_mov_b32_e32 v104, v0
	v_mov_b32_e32 v105, v0
	v_mov_b32_e32 v106, v0
	v_mov_b32_e32 v107, v0
	v_mov_b32_e32 v108, v0
	v_mov_b32_e32 v109, v0
	v_mov_b32_e32 v110, v0
	v_mov_b32_e32 v111, v0
	v_mov_b32_e32 v112, v0
	v_mov_b32_e32 v113, v0
	v_mov_b32_e32 v114, v0
	v_mov_b32_e32 v115, v0
	v_mov_b32_e32 v116, v0
	v_mov_b32_e32 v117, v0
	v_mov_b32_e32 v118, v0
	v_mov_b32_e32 v119, v0
	v_mov_b32_e32 v120, v0
	v_mov_b32_e32 v121, v0
	v_mov_b32_e32 v122, v0
	v_mov_b32_e32 v123, v0
	v_mov_b32_e32 v124, v0
	v_mov_b32_e32 v125, v0
	v_mov_b32_e32 v126, v0
	v_mov_b32_e32 v127, v0
	s_mov_b64 vcc, 0xc040180
	s_barrier
	s_barrier
	.p2align 6

.LBB0_814:
	s_or_b64 exec, exec, s[12:13]
	s_add_i32 s12, s14, 0x80
	s_ashr_i32 s13, s12, 31
	s_ashr_i32 s17, s2, 31
	s_mov_b32 s16, s2
	s_ashr_i32 s15, s14, 31
	s_lshl_b64 s[12:13], s[12:13], 14
	s_lshl_b64 s[18:19], s[16:17], 14
	s_lshl_b64 s[20:21], s[14:15], 14
	s_add_u32 s18, s26, s18
	s_addc_u32 s19, s27, s19
	s_add_u32 s20, s38, s20
	s_addc_u32 s21, s39, s21
	s_add_u32 s22, s38, s12
	v_mov_b32_e32 v0, 0
	s_addc_u32 s23, s39, s13
	s_mov_b32 s3, -2
	v_mov_b32_e32 v1, v0
	v_mov_b32_e32 v2, v0
	v_mov_b32_e32 v3, v0
	v_mov_b32_e32 v4, v0
	v_mov_b32_e32 v5, v0
	v_mov_b32_e32 v6, v0
	v_mov_b32_e32 v7, v0
	v_mov_b32_e32 v8, v0
	v_mov_b32_e32 v9, v0
	v_mov_b32_e32 v10, v0
	v_mov_b32_e32 v11, v0
	v_mov_b32_e32 v12, v0
	v_mov_b32_e32 v13, v0
	v_mov_b32_e32 v14, v0
	v_mov_b32_e32 v15, v0
	v_mov_b32_e32 v16, v0
	v_mov_b32_e32 v17, v0
	v_mov_b32_e32 v18, v0
	v_mov_b32_e32 v19, v0
	v_mov_b32_e32 v20, v0
	v_mov_b32_e32 v21, v0
	v_mov_b32_e32 v22, v0
	v_mov_b32_e32 v23, v0
	v_mov_b32_e32 v24, v0
	v_mov_b32_e32 v25, v0
	v_mov_b32_e32 v26, v0
	v_mov_b32_e32 v27, v0
	v_mov_b32_e32 v28, v0
	v_mov_b32_e32 v29, v0
	v_mov_b32_e32 v30, v0
	v_mov_b32_e32 v31, v0
	v_mov_b32_e32 v32, v0
	v_mov_b32_e32 v33, v0
	v_mov_b32_e32 v34, v0
	v_mov_b32_e32 v35, v0
	v_mov_b32_e32 v36, v0
	v_mov_b32_e32 v37, v0
	v_mov_b32_e32 v38, v0
	v_mov_b32_e32 v39, v0
	v_mov_b32_e32 v40, v0
	v_mov_b32_e32 v41, v0
	v_mov_b32_e32 v42, v0
	v_mov_b32_e32 v43, v0
	v_mov_b32_e32 v44, v0
	v_mov_b32_e32 v45, v0
	v_mov_b32_e32 v46, v0
	v_mov_b32_e32 v47, v0
	v_mov_b32_e32 v48, v0
	v_mov_b32_e32 v49, v0
	v_mov_b32_e32 v50, v0
	v_mov_b32_e32 v51, v0
	v_mov_b32_e32 v52, v0
	v_mov_b32_e32 v53, v0
	v_mov_b32_e32 v54, v0
	v_mov_b32_e32 v55, v0
	v_mov_b32_e32 v56, v0
	v_mov_b32_e32 v57, v0
	v_mov_b32_e32 v58, v0
	v_mov_b32_e32 v59, v0
	v_mov_b32_e32 v60, v0
	v_mov_b32_e32 v61, v0
	v_mov_b32_e32 v62, v0
	v_mov_b32_e32 v63, v0
	v_mov_b32_e32 v64, v0
	v_mov_b32_e32 v65, v0
	v_mov_b32_e32 v66, v0
	v_mov_b32_e32 v67, v0
	v_mov_b32_e32 v68, v0
	v_mov_b32_e32 v69, v0
	v_mov_b32_e32 v70, v0
	v_mov_b32_e32 v71, v0
	v_mov_b32_e32 v72, v0
	v_mov_b32_e32 v73, v0
	v_mov_b32_e32 v74, v0
	v_mov_b32_e32 v75, v0
	v_mov_b32_e32 v76, v0
	v_mov_b32_e32 v77, v0
	v_mov_b32_e32 v78, v0
	v_mov_b32_e32 v79, v0
	v_mov_b32_e32 v80, v0
	v_mov_b32_e32 v81, v0
	v_mov_b32_e32 v82, v0
	v_mov_b32_e32 v83, v0
	v_mov_b32_e32 v84, v0
	v_mov_b32_e32 v85, v0
	v_mov_b32_e32 v86, v0
	v_mov_b32_e32 v87, v0
	v_mov_b32_e32 v88, v0
	v_mov_b32_e32 v89, v0
	v_mov_b32_e32 v90, v0
	v_mov_b32_e32 v91, v0
	v_mov_b32_e32 v92, v0
	v_mov_b32_e32 v93, v0
	v_mov_b32_e32 v94, v0
	v_mov_b32_e32 v95, v0
	v_mov_b32_e32 v96, v0
	v_mov_b32_e32 v97, v0
	v_mov_b32_e32 v98, v0
	v_mov_b32_e32 v99, v0
	v_mov_b32_e32 v100, v0
	v_mov_b32_e32 v101, v0
	v_mov_b32_e32 v102, v0
	v_mov_b32_e32 v103, v0
	v_mov_b32_e32 v104, v0
	v_mov_b32_e32 v105, v0
	v_mov_b32_e32 v106, v0
	v_mov_b32_e32 v107, v0
	v_mov_b32_e32 v108, v0
	v_mov_b32_e32 v109, v0
	v_mov_b32_e32 v110, v0
	v_mov_b32_e32 v111, v0
	v_mov_b32_e32 v112, v0
	v_mov_b32_e32 v113, v0
	v_mov_b32_e32 v114, v0
	v_mov_b32_e32 v115, v0
	v_mov_b32_e32 v116, v0
	v_mov_b32_e32 v117, v0
	v_mov_b32_e32 v118, v0
	v_mov_b32_e32 v119, v0
	v_mov_b32_e32 v120, v0
	v_mov_b32_e32 v121, v0
	v_mov_b32_e32 v122, v0
	v_mov_b32_e32 v123, v0
	v_mov_b32_e32 v124, v0
	v_mov_b32_e32 v125, v0
	v_mov_b32_e32 v126, v0
	v_mov_b32_e32 v127, v0
	s_mov_b64 vcc, 0x14000100
	s_mov_b64 s[76:77], 0x14000180
	s_mov_b64 s[8:9], 0x14100100
	s_barrier
	s_barrier
	.p2align 6
